# tb2 + coalesced stash layout for diff map0->map1 hand-off (per-wave 1KB-contiguous pieces, plain stores)
# speedup vs baseline: 1.0190x; 1.0125x over previous
; #define LAS __attribute__((address_space(3)))
; __device__ __forceinline__ unsigned f2bf(float f) { unsigned u = __builtin_bit_cast(unsigned, f); return (u + 0x7fffu + ((u >> 16) & 1u)) >> 16; }
; __device__ __forceinline__ int crow(int r, int hi) { return (r & 3) + 8 * (r >> 2) + 4 * hi; }
; template <bool NOMAX>
; __device__ __forceinline__ void diff_unit(const AttnCtx& C, int u, LAS unsigned char* lds) {
;     ...
;         const f32x4* st = (const f32x4*)(C.stash + (slot * 512 + tidf) * 64);
;         LAS bf16* stg = (LAS bf16*)(lds + TD_OST) + wid * (32 * 128);
; #pragma unroll
;         for (int d = 0; d < 4; ++d)
; #pragma unroll
;             for (int gq = 0; gq < 4; ++gq) { const f32x4 s1 = st[d * 4 + gq];
; #pragma unroll
;                 for (int e = 0; e < 4; ++e) { const int r = 4 * gq + e; stg[crow(r, hi) * 128 + 32 * d + r32] = (bf16)f2bf(s1[e] - C.lam * (o[d][r] * rli[r])); } }
.LBB0_532:
	s_or_b64 exec, exec, s[6:7]
	v_ashrrev_i32_e32 v9, 31, v8
	v_lshlrev_b64 v[4:5], 17, v[2:3]
	v_lshl_add_u64 v[4:5], s[12:13], 0, v[4:5]
	v_and_b32_e32 v6, 63, v8
	v_lshrrev_b32_e32 v7, 6, v8
	v_lshlrev_b32_e32 v6, 4, v6
	v_lshl_add_u32 v6, v7, 14, v6
	v_add_u32_e32 v6, 0x1000, v6
	v_mov_b32_e32 v7, 0
	s_mov_b64 s[98:99], 0x2000
	v_lshl_add_u64 v[92:93], v[4:5], 0, v[6:7]
	v_lshl_add_u64 v[254:255], v[92:93], 0, s[98:99]
	s_barrier
	global_load_dwordx4 v[96:99], v[92:93], off offset:-4096
	global_load_dwordx4 v[100:103], v[92:93], off offset:-3072
	global_load_dwordx4 v[104:107], v[92:93], off offset:-2048
	global_load_dwordx4 v[108:111], v[92:93], off offset:-1024
	global_load_dwordx4 v[4:7], v[92:93], off offset:1024
	global_load_dwordx4 v[112:115], v[92:93], off
	global_load_dwordx4 v[116:119], v[92:93], off offset:3072
	global_load_dwordx4 v[120:123], v[92:93], off offset:2048
	v_mul_f32_e32 v95, v68, v90
	s_lshl_b32 s0, s0, 1
	v_mul_f32_e32 v124, v69, v91
	v_mul_f32_e32 v125, v70, v88
	v_mul_f32_e32 v126, v71, v89
	v_mul_f32_e32 v127, v72, v14
	v_mul_f32_e32 v128, v73, v15
	v_mul_f32_e32 v129, v74, v86
	v_mul_f32_e32 v130, v75, v87
	v_mul_f32_e32 v131, v76, v84
	v_mul_f32_e32 v132, v77, v85
	v_mul_f32_e32 v133, v78, v16
	v_mul_f32_e32 v134, v79, v17
	v_mul_f32_e32 v135, v80, v12
	v_mul_f32_e32 v136, v81, v13
	v_lshlrev_b32_e32 v9, 1, v210
	s_add_i32 s0, s0, 0
	v_add3_u32 v9, s0, v9, v201
	v_readlane_b32 s8, v253, 60
	v_readlane_b32 s9, v253, 61
	v_mov_b32_e32 v219, v3
	v_readlane_b32 s60, v253, 32
	v_readlane_b32 s72, v253, 44
	v_readlane_b32 s73, v253, 45
	v_readlane_b32 s6, v253, 28
	v_readlane_b32 s7, v253, 29
	v_readlane_b32 s61, v253, 33
	v_readlane_b32 s62, v253, 34
	v_readlane_b32 s63, v253, 35
	v_readlane_b32 s64, v253, 36
	v_readlane_b32 s65, v253, 37
	v_readlane_b32 s66, v253, 38
	v_readlane_b32 s67, v253, 39
	v_readlane_b32 s68, v253, 40
	v_readlane_b32 s69, v253, 41
	v_readlane_b32 s70, v253, 42
	v_readlane_b32 s71, v253, 43
	v_readlane_b32 s74, v253, 46
	v_readlane_b32 s75, v253, 47
	s_waitcnt vmcnt(7)
	v_fma_f32 v95, -v216, v95, v96
	v_fma_f32 v96, -v216, v124, v97
	v_fma_f32 v97, -v216, v125, v98
	v_fma_f32 v98, -v216, v126, v99
	s_waitcnt vmcnt(6)
	v_fma_f32 v99, -v216, v127, v100
	v_fma_f32 v100, -v216, v128, v101
	v_fma_f32 v101, -v216, v129, v102
	v_fma_f32 v102, -v216, v130, v103
	s_waitcnt vmcnt(5)
	v_fma_f32 v103, -v216, v131, v104
	v_fma_f32 v104, -v216, v132, v105
	v_fma_f32 v105, -v216, v133, v106
	v_fma_f32 v106, -v216, v134, v107
	s_waitcnt vmcnt(4)
	v_fma_f32 v107, -v216, v135, v108
	v_fma_f32 v108, -v216, v136, v109
	v_bfe_u32 v109, v95, 16, 1
	v_bfe_u32 v124, v96, 16, 1
	v_bfe_u32 v125, v97, 16, 1
	v_bfe_u32 v126, v98, 16, 1
	v_bfe_u32 v127, v99, 16, 1
	v_bfe_u32 v128, v100, 16, 1
	v_bfe_u32 v129, v101, 16, 1
	v_bfe_u32 v130, v102, 16, 1
	v_bfe_u32 v131, v103, 16, 1
	v_bfe_u32 v132, v104, 16, 1
	v_bfe_u32 v133, v105, 16, 1
	v_bfe_u32 v134, v106, 16, 1
	v_bfe_u32 v135, v107, 16, 1
	v_add3_u32 v95, v95, v109, s55
	v_add3_u32 v96, v96, v124, s55
	v_add3_u32 v97, v97, v125, s55
	v_add3_u32 v98, v98, v126, s55
	v_add3_u32 v99, v99, v127, s55
	v_add3_u32 v100, v100, v128, s55
	v_add3_u32 v101, v101, v129, s55
	v_add3_u32 v102, v102, v130, s55
	v_add3_u32 v103, v103, v131, s55
	v_add3_u32 v104, v104, v132, s55
	v_add3_u32 v105, v105, v133, s55
	v_add3_u32 v106, v106, v134, s55
	v_add3_u32 v107, v107, v135, s55
	ds_write_b16_d16_hi v9, v95
	ds_write_b16_d16_hi v9, v96 offset:256
	ds_write_b16_d16_hi v9, v97 offset:512
	ds_write_b16_d16_hi v9, v98 offset:768
	ds_write_b16_d16_hi v9, v99 offset:2048
	ds_write_b16_d16_hi v9, v100 offset:2304
	ds_write_b16_d16_hi v9, v101 offset:2560
	ds_write_b16_d16_hi v9, v102 offset:2816
	ds_write_b16_d16_hi v9, v103 offset:4096
	ds_write_b16_d16_hi v9, v104 offset:4352
	ds_write_b16_d16_hi v9, v105 offset:4608
	ds_write_b16_d16_hi v9, v106 offset:4864
	ds_write_b16_d16_hi v9, v107 offset:6144
	v_bfe_u32 v95, v108, 16, 1
	v_add3_u32 v95, v108, v95, s55
	ds_write_b16_d16_hi v9, v95 offset:6400
	v_mul_f32_e32 v95, v82, v10
	v_fma_f32 v95, -v216, v95, v110
	v_bfe_u32 v96, v95, 16, 1
	v_add3_u32 v95, v95, v96, s55
	ds_write_b16_d16_hi v9, v95 offset:6656
	v_mul_f32_e32 v95, v83, v11
	v_fma_f32 v95, -v216, v95, v111
	v_bfe_u32 v96, v95, 16, 1
	v_add3_u32 v95, v95, v96, s55
	ds_write_b16_d16_hi v9, v95 offset:6912
	v_mul_f32_e32 v95, v52, v90
	s_waitcnt vmcnt(2)
	v_fma_f32 v95, -v216, v95, v112
	v_bfe_u32 v96, v95, 16, 1
	v_add3_u32 v95, v95, v96, s55
	global_load_dwordx4 v[96:99], v[254:255], off offset:-3072
	global_load_dwordx4 v[100:103], v[254:255], off offset:-4096
	ds_write_b16_d16_hi v9, v95 offset:64
	v_mul_f32_e32 v95, v53, v91
	v_fma_f32 v95, -v216, v95, v113
	v_bfe_u32 v104, v95, 16, 1
	v_add3_u32 v95, v95, v104, s55
	ds_write_b16_d16_hi v9, v95 offset:320
	v_mul_f32_e32 v95, v54, v88
	v_fma_f32 v95, -v216, v95, v114
	v_bfe_u32 v104, v95, 16, 1
	v_add3_u32 v95, v95, v104, s55
	ds_write_b16_d16_hi v9, v95 offset:576
	v_mul_f32_e32 v95, v55, v89
	v_fma_f32 v95, -v216, v95, v115
	v_bfe_u32 v104, v95, 16, 1
	v_add3_u32 v95, v95, v104, s55
	ds_write_b16_d16_hi v9, v95 offset:832
	v_mul_f32_e32 v95, v56, v14
	v_fma_f32 v4, -v216, v95, v4
	v_bfe_u32 v95, v4, 16, 1
	v_add3_u32 v4, v4, v95, s55
	ds_write_b16_d16_hi v9, v4 offset:2112
	v_mul_f32_e32 v4, v57, v15
	v_fma_f32 v4, -v216, v4, v5
	v_bfe_u32 v5, v4, 16, 1
	v_add3_u32 v4, v4, v5, s55
	ds_write_b16_d16_hi v9, v4 offset:2368
	v_mul_f32_e32 v4, v58, v86
	v_fma_f32 v4, -v216, v4, v6
	v_bfe_u32 v5, v4, 16, 1
	v_add3_u32 v4, v4, v5, s55
	ds_write_b16_d16_hi v9, v4 offset:2624
	v_mul_f32_e32 v4, v59, v87
	v_fma_f32 v4, -v216, v4, v7
	v_bfe_u32 v5, v4, 16, 1
	v_add3_u32 v4, v4, v5, s55
	ds_write_b16_d16_hi v9, v4 offset:2880
	v_mul_f32_e32 v4, v60, v84
	s_waitcnt vmcnt(2)
; #define LAS __attribute__((address_space(3)))
; __device__ __forceinline__ unsigned f2bf(float f) { unsigned u = __builtin_bit_cast(unsigned, f); return (u + 0x7fffu + ((u >> 16) & 1u)) >> 16; }
; __device__ __forceinline__ int crow(int r, int hi) { return (r & 3) + 8 * (r >> 2) + 4 * hi; }
; template <bool NOMAX>
; __device__ __forceinline__ void diff_unit(const AttnCtx& C, int u, LAS unsigned char* lds) {
;     ...
;         const f32x4* st = (const f32x4*)(C.stash + (slot * 512 + tidf) * 64);
;         LAS bf16* stg = (LAS bf16*)(lds + TD_OST) + wid * (32 * 128);
; #pragma unroll
;         for (int d = 0; d < 4; ++d)
; #pragma unroll
;             for (int gq = 0; gq < 4; ++gq) { const f32x4 s1 = st[d * 4 + gq];
; #pragma unroll
;                 for (int e = 0; e < 4; ++e) { const int r = 4 * gq + e; stg[crow(r, hi) * 128 + 32 * d + r32] = (bf16)f2bf(s1[e] - C.lam * (o[d][r] * rli[r])); } }
	v_fma_f32 v4, -v216, v4, v120
	v_bfe_u32 v5, v4, 16, 1
	v_add3_u32 v95, v4, v5, s55
	global_load_dwordx4 v[4:7], v[254:255], off offset:-1024
	global_load_dwordx4 v[104:107], v[254:255], off offset:-2048
	ds_write_b16_d16_hi v9, v95 offset:4160
	v_mul_f32_e32 v95, v61, v85
	v_fma_f32 v95, -v216, v95, v121
	v_bfe_u32 v108, v95, 16, 1
	v_add3_u32 v95, v95, v108, s55
	ds_write_b16_d16_hi v9, v95 offset:4416
	v_mul_f32_e32 v95, v62, v16
	v_fma_f32 v95, -v216, v95, v122
	v_bfe_u32 v108, v95, 16, 1
	v_add3_u32 v95, v95, v108, s55
	ds_write_b16_d16_hi v9, v95 offset:4672
	v_mul_f32_e32 v95, v63, v17
	v_fma_f32 v95, -v216, v95, v123
	v_bfe_u32 v108, v95, 16, 1
	v_add3_u32 v95, v95, v108, s55
	ds_write_b16_d16_hi v9, v95 offset:4928
	v_mul_f32_e32 v95, v64, v12
	v_fma_f32 v95, -v216, v95, v116
	v_bfe_u32 v108, v95, 16, 1
	v_add3_u32 v95, v95, v108, s55
	ds_write_b16_d16_hi v9, v95 offset:6208
	v_mul_f32_e32 v95, v65, v13
	v_fma_f32 v95, -v216, v95, v117
	v_bfe_u32 v108, v95, 16, 1
	v_add3_u32 v95, v95, v108, s55
	ds_write_b16_d16_hi v9, v95 offset:6464
	v_mul_f32_e32 v95, v66, v10
	v_fma_f32 v95, -v216, v95, v118
	v_bfe_u32 v108, v95, 16, 1
	v_add3_u32 v95, v95, v108, s55
	ds_write_b16_d16_hi v9, v95 offset:6720
	v_mul_f32_e32 v95, v67, v11
	v_fma_f32 v95, -v216, v95, v119
	v_bfe_u32 v108, v95, 16, 1
	v_add3_u32 v95, v95, v108, s55
	ds_write_b16_d16_hi v9, v95 offset:6976
	v_mul_f32_e32 v95, v36, v90
	global_load_dwordx4 v[108:111], v[254:255], off offset:1024
	global_load_dwordx4 v[112:115], v[254:255], off
	s_waitcnt vmcnt(4)
	v_fma_f32 v95, -v216, v95, v100
	v_bfe_u32 v100, v95, 16, 1
	v_add3_u32 v95, v95, v100, s55
	ds_write_b16_d16_hi v9, v95 offset:128
	v_mul_f32_e32 v95, v37, v91
	v_fma_f32 v95, -v216, v95, v101
	v_bfe_u32 v100, v95, 16, 1
	v_add3_u32 v95, v95, v100, s55
	ds_write_b16_d16_hi v9, v95 offset:384
	v_mul_f32_e32 v95, v38, v88
	v_fma_f32 v95, -v216, v95, v102
	v_bfe_u32 v100, v95, 16, 1
	v_add3_u32 v95, v95, v100, s55
	ds_write_b16_d16_hi v9, v95 offset:640
	v_mul_f32_e32 v95, v39, v89
	v_fma_f32 v95, -v216, v95, v103
	v_bfe_u32 v100, v95, 16, 1
	v_add3_u32 v95, v95, v100, s55
	ds_write_b16_d16_hi v9, v95 offset:896
	v_mul_f32_e32 v95, v40, v14
	v_fma_f32 v95, -v216, v95, v96
	v_bfe_u32 v96, v95, 16, 1
	v_add3_u32 v95, v95, v96, s55
	ds_write_b16_d16_hi v9, v95 offset:2176
	v_mul_f32_e32 v95, v41, v15
	v_fma_f32 v95, -v216, v95, v97
	v_bfe_u32 v96, v95, 16, 1
	v_add3_u32 v95, v95, v96, s55
	ds_write_b16_d16_hi v9, v95 offset:2432
	v_mul_f32_e32 v95, v42, v86
	v_fma_f32 v95, -v216, v95, v98
	v_bfe_u32 v96, v95, 16, 1
	v_add3_u32 v95, v95, v96, s55
	ds_write_b16_d16_hi v9, v95 offset:2688
	v_mul_f32_e32 v95, v43, v87
	v_fma_f32 v95, -v216, v95, v99
	v_bfe_u32 v96, v95, 16, 1
	v_add3_u32 v95, v95, v96, s55
	ds_write_b16_d16_hi v9, v95 offset:2944
	global_load_dwordx4 v[96:99], v[254:255], off offset:3072
	global_load_dwordx4 v[100:103], v[254:255], off offset:2048
	v_mul_f32_e32 v95, v44, v84
	s_waitcnt vmcnt(4)
	v_fma_f32 v95, -v216, v95, v104
	v_bfe_u32 v92, v95, 16, 1
	v_add3_u32 v92, v95, v92, s55
	ds_write_b16_d16_hi v9, v92 offset:4224
	v_mul_f32_e32 v92, v45, v85
	v_fma_f32 v92, -v216, v92, v105
	v_bfe_u32 v93, v92, 16, 1
	v_add3_u32 v92, v92, v93, s55
	ds_write_b16_d16_hi v9, v92 offset:4480
	v_mul_f32_e32 v92, v46, v16
	v_fma_f32 v92, -v216, v92, v106
	v_bfe_u32 v93, v92, 16, 1
	v_add3_u32 v92, v92, v93, s55
	ds_write_b16_d16_hi v9, v92 offset:4736
	v_mul_f32_e32 v92, v47, v17
	v_fma_f32 v92, -v216, v92, v107
	v_bfe_u32 v93, v92, 16, 1
	v_add3_u32 v92, v92, v93, s55
	ds_write_b16_d16_hi v9, v92 offset:4992
	v_mul_f32_e32 v92, v48, v12
	v_fma_f32 v4, -v216, v92, v4
	v_bfe_u32 v92, v4, 16, 1
	v_add3_u32 v4, v4, v92, s55
	ds_write_b16_d16_hi v9, v4 offset:6272
	v_mul_f32_e32 v4, v49, v13
	v_fma_f32 v4, -v216, v4, v5
	v_bfe_u32 v5, v4, 16, 1
	v_add3_u32 v4, v4, v5, s55
	ds_write_b16_d16_hi v9, v4 offset:6528
	v_mul_f32_e32 v4, v50, v10
	v_fma_f32 v4, -v216, v4, v6
	v_bfe_u32 v5, v4, 16, 1
	v_add3_u32 v4, v4, v5, s55
	ds_write_b16_d16_hi v9, v4 offset:6784
	v_mul_f32_e32 v4, v51, v11
	v_fma_f32 v4, -v216, v4, v7
	v_bfe_u32 v5, v4, 16, 1
	v_add3_u32 v4, v4, v5, s55
	ds_write_b16_d16_hi v9, v4 offset:7040
	v_mul_f32_e32 v4, v20, v90
	s_waitcnt vmcnt(2)
	v_fma_f32 v4, -v216, v4, v112
	v_bfe_u32 v5, v4, 16, 1
	v_add3_u32 v4, v4, v5, s55
	ds_write_b16_d16_hi v9, v4 offset:192
	v_mul_f32_e32 v4, v21, v91
	v_fma_f32 v4, -v216, v4, v113
	v_bfe_u32 v5, v4, 16, 1
	v_add3_u32 v4, v4, v5, s55
	ds_write_b16_d16_hi v9, v4 offset:448
	v_mul_f32_e32 v4, v22, v88
	v_fma_f32 v4, -v216, v4, v114
	v_bfe_u32 v5, v4, 16, 1
	v_add3_u32 v4, v4, v5, s55
	ds_write_b16_d16_hi v9, v4 offset:704
	v_mul_f32_e32 v4, v23, v89
	v_fma_f32 v4, -v216, v4, v115
	v_bfe_u32 v5, v4, 16, 1
	v_add3_u32 v4, v4, v5, s55
	ds_write_b16_d16_hi v9, v4 offset:960
	v_mul_f32_e32 v4, v24, v14
	v_fma_f32 v4, -v216, v4, v108
	v_bfe_u32 v5, v4, 16, 1
	v_add3_u32 v4, v4, v5, s55
	ds_write_b16_d16_hi v9, v4 offset:2240
	v_mul_f32_e32 v4, v25, v15
	v_fma_f32 v4, -v216, v4, v109
	v_bfe_u32 v5, v4, 16, 1
	v_add3_u32 v4, v4, v5, s55
	ds_write_b16_d16_hi v9, v4 offset:2496
	v_mul_f32_e32 v4, v26, v86
	v_fma_f32 v4, -v216, v4, v110
	v_bfe_u32 v5, v4, 16, 1
	v_add3_u32 v4, v4, v5, s55
	ds_write_b16_d16_hi v9, v4 offset:2752
	v_mul_f32_e32 v4, v27, v87
	v_fma_f32 v4, -v216, v4, v111
	v_bfe_u32 v5, v4, 16, 1
	v_add3_u32 v4, v4, v5, s55
	ds_write_b16_d16_hi v9, v4 offset:3008
	v_mul_f32_e32 v4, v28, v84
	s_waitcnt vmcnt(0)
; template <bool NOMAX>
; __device__ __forceinline__ void diff_unit(const AttnCtx& C, int u, LAS unsigned char* lds) {
;     ...
;                 for (int e = 0; e < 4; ++e) { const int r = 4 * gq + e; stg[crow(r, hi) * 128 + 32 * d + r32] = (bf16)f2bf(s1[e] - C.lam * (o[d][r] * rli[r])); } }
;         LDS_WAIT(); asm volatile("" ::: "memory");
;         const int cl = lanef & 15;
;         const size_t rowb = (size_t)(q0 + wid * 32);
; #pragma unroll
;         for (int ps = 0; ps < 8; ++ps) {
;             const int rl = ps * 4 + (lanef >> 4); const size_t row = rowb + rl;
;             const v4u sv = *(const LAS v4u*)(stg + rl * 128 + cl * 8);
;             float xv[8];
;             xv[0] = __builtin_bit_cast(float, sv.x << 16); xv[1] = __builtin_bit_cast(float, sv.x & 0xffff0000u); xv[2] = __builtin_bit_cast(float, sv.y << 16); xv[3] = __builtin_bit_cast(float, sv.y & 0xffff0000u);
;             xv[4] = __builtin_bit_cast(float, sv.z << 16); xv[5] = __builtin_bit_cast(float, sv.z & 0xffff0000u); xv[6] = __builtin_bit_cast(float, sv.w << 16); xv[7] = __builtin_bit_cast(float, sv.w & 0xffff0000u);
;             const v4u gv = *(const v4u*)(C.GD + row * 512 + h * 128 + cl * 8);
;             float gg[8];
;             gg[0] = __builtin_bit_cast(float, gv.x << 16); gg[1] = __builtin_bit_cast(float, gv.x & 0xffff0000u); gg[2] = __builtin_bit_cast(float, gv.y << 16); gg[3] = __builtin_bit_cast(float, gv.y & 0xffff0000u);
;             gg[4] = __builtin_bit_cast(float, gv.z << 16); gg[5] = __builtin_bit_cast(float, gv.z & 0xffff0000u); gg[6] = __builtin_bit_cast(float, gv.w << 16); gg[7] = __builtin_bit_cast(float, gv.w & 0xffff0000u);
;             float sq = 0.f;
; #pragma unroll
;             for (int e = 0; e < 8; ++e) sq += xv[e] * xv[e];
;     ...
;             SQDPP(0xB1); SQDPP(0x4E); SQDPP(0x141); SQDPP(0x140);
;     ...
;             const float rs = (1.0f / sqrtf(sq * (1.0f / 128.0f) + EPSN)) * 0.8f;
;             const f32x4 s0 = *(const f32x4*)(C.subln + cl * 8), s1 = *(const f32x4*)(C.subln + cl * 8 + 4);
; #pragma unroll
;             for (int e = 0; e < 4; ++e) { xv[e] *= rs * s0[e]; xv[4 + e] *= rs * s1[e]; }
;             v4u ov; ov.x = pk2(xv[0] * gg[0], xv[1] * gg[1]); ov.y = pk2(xv[2] * gg[2], xv[3] * gg[3]); ov.z = pk2(xv[4] * gg[4], xv[5] * gg[5]); ov.w = pk2(xv[6] * gg[6], xv[7] * gg[7]);
;             *(v4u*)(C.MIX + row * 1024 + 512 + h * 128 + cl * 8) = ov;
	v_fma_f32 v4, -v216, v4, v100
	v_bfe_u32 v5, v4, 16, 1
	v_add3_u32 v4, v4, v5, s55
	ds_write_b16_d16_hi v9, v4 offset:4288
	v_mul_f32_e32 v4, v29, v85
	v_fma_f32 v4, -v216, v4, v101
	v_bfe_u32 v5, v4, 16, 1
	v_add3_u32 v4, v4, v5, s55
	ds_write_b16_d16_hi v9, v4 offset:4544
	v_mul_f32_e32 v4, v30, v16
	v_fma_f32 v4, -v216, v4, v102
	v_bfe_u32 v5, v4, 16, 1
	v_add3_u32 v4, v4, v5, s55
	ds_write_b16_d16_hi v9, v4 offset:4800
	v_mul_f32_e32 v4, v31, v17
	v_fma_f32 v4, -v216, v4, v103
	v_bfe_u32 v5, v4, 16, 1
	v_add3_u32 v4, v4, v5, s55
	ds_write_b16_d16_hi v9, v4 offset:5056
	v_mul_f32_e32 v4, v32, v12
	v_fma_f32 v4, -v216, v4, v96
	v_bfe_u32 v5, v4, 16, 1
	v_add3_u32 v4, v4, v5, s55
	ds_write_b16_d16_hi v9, v4 offset:6336
	v_mul_f32_e32 v4, v33, v13
	v_fma_f32 v4, -v216, v4, v97
	v_bfe_u32 v5, v4, 16, 1
	v_add3_u32 v4, v4, v5, s55
	ds_write_b16_d16_hi v9, v4 offset:6592
	v_mul_f32_e32 v4, v34, v10
	v_fma_f32 v4, -v216, v4, v98
	v_bfe_u32 v5, v4, 16, 1
	v_add3_u32 v4, v4, v5, s55
	ds_write_b16_d16_hi v9, v4 offset:6848
	v_mul_f32_e32 v4, v35, v11
	v_fma_f32 v4, -v216, v4, v99
	v_bfe_u32 v5, v4, 16, 1
	v_bfe_u32 v6, v8, 4, 2
	v_add3_u32 v4, v4, v5, s55
	v_or_b32_e32 v92, v202, v6
	v_mov_b32_e32 v93, v203
	ds_write_b16_d16_hi v9, v4 offset:7104
	v_lshlrev_b32_e32 v4, 3, v8
	v_lshlrev_b64 v[96:97], 10, v[92:93]
	v_and_b32_e32 v7, 0x78, v4
	v_lshl_add_u64 v[96:97], s[8:9], 0, v[96:97]
	s_waitcnt lgkmcnt(0)
	v_lshlrev_b32_e32 v4, 1, v7
	v_lshl_add_u64 v[96:97], v[96:97], 0, v[218:219]
	v_mov_b32_e32 v5, v3
	v_lshl_add_u64 v[96:97], v[96:97], 0, v[4:5]
	global_load_dwordx4 v[96:99], v[96:97], off
	v_lshlrev_b32_e32 v7, 2, v7
	global_load_dwordx4 v[100:103], v7, s[72:73]
	global_load_dwordx4 v[104:107], v7, s[72:73] offset:16
	v_add_u32_e32 v9, s0, v4
	v_lshl_add_u32 v95, v6, 8, v9
	ds_read_b128 v[108:111], v95
	v_lshlrev_b64 v[92:93], 11, v[92:93]
	v_lshl_add_u64 v[92:93], s[6:7], 0, v[92:93]
	v_lshl_add_u64 v[92:93], v[92:93], 0, v[218:219]
	v_lshl_add_u64 v[92:93], v[92:93], 0, v[4:5]
	s_waitcnt lgkmcnt(0)
	v_lshlrev_b32_e32 v124, 16, v108
	v_and_b32_e32 v125, 0xffff0000, v108
	v_lshlrev_b32_e32 v120, 16, v109
	v_and_b32_e32 v121, 0xffff0000, v109
	v_pk_mul_f32 v[108:109], v[124:125], v[124:125]
	v_pk_mul_f32 v[122:123], v[120:121], v[120:121]
	v_add_f32_e32 v95, v108, v109
	v_lshlrev_b32_e32 v118, 16, v110
	v_and_b32_e32 v119, 0xffff0000, v110
	v_add_f32_e32 v95, v122, v95
	v_lshlrev_b32_e32 v112, 16, v111
	v_and_b32_e32 v113, 0xffff0000, v111
	v_pk_mul_f32 v[110:111], v[118:119], v[118:119]
	v_add_f32_e32 v95, v123, v95
	v_add_f32_e32 v95, v110, v95
	v_pk_mul_f32 v[116:117], v[112:113], v[112:113]
	v_add_f32_e32 v95, v111, v95
	v_add_f32_e32 v95, v116, v95
	v_add_f32_e32 v95, v117, v95
	s_waitcnt vmcnt(2)
	v_lshlrev_b32_e32 v114, 16, v99
	v_add_f32_dpp v95, v95, v95 quad_perm:[1,0,3,2] row_mask:0xf bank_mask:0xf bound_ctrl:1
	v_and_b32_e32 v115, 0xffff0000, v99
	v_lshlrev_b32_e32 v108, 16, v98
	v_add_f32_dpp v95, v95, v95 quad_perm:[2,3,0,1] row_mask:0xf bank_mask:0xf bound_ctrl:1
	v_and_b32_e32 v109, 0xffff0000, v98
	v_lshlrev_b32_e32 v98, 16, v97
	v_add_f32_dpp v95, v95, v95 row_half_mirror row_mask:0xf bank_mask:0xf bound_ctrl:1
	s_nop 1
	v_add_f32_dpp v95, v95, v95 row_mirror row_mask:0xf bank_mask:0xf bound_ctrl:1
	v_fmamk_f32 v95, v95, 0x3c000000, v217
	v_mul_f32_e32 v99, 0x4f800000, v95
	v_cmp_gt_f32_e32 vcc, s56, v95
	s_nop 1
	v_cndmask_b32_e32 v95, v95, v99, vcc
	v_sqrt_f32_e32 v99, v95
	s_nop 0
	v_add_u32_e32 v110, -1, v99
	v_fma_f32 v111, -v110, v99, v95
	v_cmp_ge_f32_e64 s[4:5], 0, v111
	v_add_u32_e32 v111, 1, v99
	s_nop 0
	v_cndmask_b32_e64 v110, v99, v110, s[4:5]
	v_fma_f32 v99, -v111, v99, v95
	v_cmp_lt_f32_e64 s[4:5], 0, v99
	s_nop 1
	v_cndmask_b32_e64 v99, v110, v111, s[4:5]
	v_mul_f32_e32 v110, 0x37800000, v99
	v_cndmask_b32_e32 v99, v99, v110, vcc
	v_cmp_class_f32_e32 vcc, v95, v228
	v_lshlrev_b32_e32 v110, 16, v96
	v_and_b32_e32 v111, 0xffff0000, v96
	v_cndmask_b32_e32 v95, v99, v95, vcc
	v_div_scale_f32 v116, s[0:1], v95, v95, 1.0
	v_rcp_f32_e32 v117, v116
	v_and_b32_e32 v99, 0xffff0000, v97
	v_fma_f32 v96, -v116, v117, 1.0
	v_fmac_f32_e32 v117, v96, v117
	v_div_scale_f32 v96, vcc, 1.0, v95, 1.0
	v_mul_f32_e32 v97, v96, v117
	v_fma_f32 v122, -v116, v97, v96
	v_fmac_f32_e32 v97, v122, v117
	v_fma_f32 v96, -v116, v97, v96
	v_div_fmas_f32 v96, v96, v117, v97
	v_div_fixup_f32 v95, v96, v95, 1.0
	v_mul_f32_e32 v96, 0x3f4ccccd, v95
	s_waitcnt vmcnt(1)
	v_pk_mul_f32 v[100:101], v[100:101], v[96:97] op_sel_hi:[1,0]
	v_pk_mul_f32 v[102:103], v[102:103], v[96:97] op_sel_hi:[1,0]
	v_pk_mul_f32 v[100:101], v[100:101], v[124:125]
	s_waitcnt vmcnt(0)
	v_pk_mul_f32 v[104:105], v[104:105], v[96:97] op_sel_hi:[1,0]
	v_pk_mul_f32 v[102:103], v[102:103], v[120:121]
	v_pk_mul_f32 v[96:97], v[106:107], v[96:97] op_sel_hi:[1,0]
	v_pk_mul_f32 v[104:105], v[104:105], v[118:119]
	v_pk_mul_f32 v[106:107], v[96:97], v[112:113]
	v_pk_mul_f32 v[96:97], v[100:101], v[110:111]
	v_pk_mul_f32 v[98:99], v[102:103], v[98:99]
	v_cvt_pk_bf16_f32 v96, v96, v97
	v_cvt_pk_bf16_f32 v97, v98, v99
	v_pk_mul_f32 v[98:99], v[104:105], v[108:109]
	v_pk_mul_f32 v[100:101], v[106:107], v[114:115]
	v_cvt_pk_bf16_f32 v98, v98, v99
	v_cvt_pk_bf16_f32 v99, v100, v101
	v_or_b32_e32 v95, 4, v6
	global_store_dwordx4 v[92:93], v[96:99], off offset:1024
	v_or_b32_e32 v92, v202, v95
	v_mov_b32_e32 v93, v203
	v_lshlrev_b64 v[96:97], 10, v[92:93]
	v_lshl_add_u64 v[96:97], s[8:9], 0, v[96:97]
	v_lshl_add_u64 v[96:97], v[96:97], 0, v[218:219]
	v_lshl_add_u64 v[96:97], v[96:97], 0, v[4:5]
	global_load_dwordx4 v[96:99], v[96:97], off
	s_nop 0
	global_load_dwordx4 v[100:103], v7, s[72:73]
	global_load_dwordx4 v[104:107], v7, s[72:73] offset:16
	v_lshl_add_u32 v95, v95, 8, v9
	ds_read_b128 v[108:111], v95
	v_lshlrev_b64 v[92:93], 11, v[92:93]
	v_lshl_add_u64 v[92:93], s[6:7], 0, v[92:93]
	v_lshl_add_u64 v[92:93], v[92:93], 0, v[218:219]
	v_lshl_add_u64 v[92:93], v[92:93], 0, v[4:5]
	s_waitcnt lgkmcnt(0)
; #define LAS __attribute__((address_space(3)))
; __device__ __forceinline__ unsigned pk2(float lo, float hi) { f32x2_t v = {lo, hi}; bf16x2_t b = __builtin_convertvector(v, bf16x2_t); return __builtin_bit_cast(unsigned, b); }
; template <bool NOMAX>
; __device__ __forceinline__ void diff_unit(const AttnCtx& C, int u, LAS unsigned char* lds) {
;     ...
;         for (int ps = 0; ps < 8; ++ps) {
;             const int rl = ps * 4 + (lanef >> 4); const size_t row = rowb + rl;
;             const v4u sv = *(const LAS v4u*)(stg + rl * 128 + cl * 8);
;             float xv[8];
;             xv[0] = __builtin_bit_cast(float, sv.x << 16); xv[1] = __builtin_bit_cast(float, sv.x & 0xffff0000u); xv[2] = __builtin_bit_cast(float, sv.y << 16); xv[3] = __builtin_bit_cast(float, sv.y & 0xffff0000u);
;             xv[4] = __builtin_bit_cast(float, sv.z << 16); xv[5] = __builtin_bit_cast(float, sv.z & 0xffff0000u); xv[6] = __builtin_bit_cast(float, sv.w << 16); xv[7] = __builtin_bit_cast(float, sv.w & 0xffff0000u);
;             const v4u gv = *(const v4u*)(C.GD + row * 512 + h * 128 + cl * 8);
;             float gg[8];
;             gg[0] = __builtin_bit_cast(float, gv.x << 16); gg[1] = __builtin_bit_cast(float, gv.x & 0xffff0000u); gg[2] = __builtin_bit_cast(float, gv.y << 16); gg[3] = __builtin_bit_cast(float, gv.y & 0xffff0000u);
;             gg[4] = __builtin_bit_cast(float, gv.z << 16); gg[5] = __builtin_bit_cast(float, gv.z & 0xffff0000u); gg[6] = __builtin_bit_cast(float, gv.w << 16); gg[7] = __builtin_bit_cast(float, gv.w & 0xffff0000u);
;             float sq = 0.f;
; #pragma unroll
;             for (int e = 0; e < 8; ++e) sq += xv[e] * xv[e];
;     ...
;             SQDPP(0xB1); SQDPP(0x4E); SQDPP(0x141); SQDPP(0x140);
;     ...
;             const float rs = (1.0f / sqrtf(sq * (1.0f / 128.0f) + EPSN)) * 0.8f;
;             const f32x4 s0 = *(const f32x4*)(C.subln + cl * 8), s1 = *(const f32x4*)(C.subln + cl * 8 + 4);
; #pragma unroll
;             for (int e = 0; e < 4; ++e) { xv[e] *= rs * s0[e]; xv[4 + e] *= rs * s1[e]; }
;             v4u ov; ov.x = pk2(xv[0] * gg[0], xv[1] * gg[1]); ov.y = pk2(xv[2] * gg[2], xv[3] * gg[3]); ov.z = pk2(xv[4] * gg[4], xv[5] * gg[5]); ov.w = pk2(xv[6] * gg[6], xv[7] * gg[7]);
;             *(v4u*)(C.MIX + row * 1024 + 512 + h * 128 + cl * 8) = ov;
	v_lshlrev_b32_e32 v124, 16, v108
	v_and_b32_e32 v125, 0xffff0000, v108
	v_lshlrev_b32_e32 v120, 16, v109
	v_and_b32_e32 v121, 0xffff0000, v109
	v_pk_mul_f32 v[108:109], v[124:125], v[124:125]
	v_pk_mul_f32 v[122:123], v[120:121], v[120:121]
	v_add_f32_e32 v95, v108, v109
	v_lshlrev_b32_e32 v118, 16, v110
	v_and_b32_e32 v119, 0xffff0000, v110
	v_add_f32_e32 v95, v122, v95
	v_lshlrev_b32_e32 v112, 16, v111
	v_and_b32_e32 v113, 0xffff0000, v111
	v_pk_mul_f32 v[110:111], v[118:119], v[118:119]
	v_add_f32_e32 v95, v123, v95
	v_add_f32_e32 v95, v110, v95
	v_pk_mul_f32 v[116:117], v[112:113], v[112:113]
	v_add_f32_e32 v95, v111, v95
	v_add_f32_e32 v95, v116, v95
	v_add_f32_e32 v95, v117, v95
	s_waitcnt vmcnt(2)
	v_lshlrev_b32_e32 v114, 16, v99
	v_add_f32_dpp v95, v95, v95 quad_perm:[1,0,3,2] row_mask:0xf bank_mask:0xf bound_ctrl:1
	v_and_b32_e32 v115, 0xffff0000, v99
	v_lshlrev_b32_e32 v108, 16, v98
	v_add_f32_dpp v95, v95, v95 quad_perm:[2,3,0,1] row_mask:0xf bank_mask:0xf bound_ctrl:1
	v_and_b32_e32 v109, 0xffff0000, v98
	v_lshlrev_b32_e32 v98, 16, v97
	v_add_f32_dpp v95, v95, v95 row_half_mirror row_mask:0xf bank_mask:0xf bound_ctrl:1
	s_nop 1
	v_add_f32_dpp v95, v95, v95 row_mirror row_mask:0xf bank_mask:0xf bound_ctrl:1
	v_fmamk_f32 v95, v95, 0x3c000000, v217
	v_mul_f32_e32 v99, 0x4f800000, v95
	v_cmp_gt_f32_e32 vcc, s56, v95
	s_nop 1
	v_cndmask_b32_e32 v95, v95, v99, vcc
	v_sqrt_f32_e32 v99, v95
	s_nop 0
	v_add_u32_e32 v110, -1, v99
	v_fma_f32 v111, -v110, v99, v95
	v_cmp_ge_f32_e64 s[4:5], 0, v111
	v_add_u32_e32 v111, 1, v99
	s_nop 0
	v_cndmask_b32_e64 v110, v99, v110, s[4:5]
	v_fma_f32 v99, -v111, v99, v95
	v_cmp_lt_f32_e64 s[4:5], 0, v99
	s_nop 1
	v_cndmask_b32_e64 v99, v110, v111, s[4:5]
	v_mul_f32_e32 v110, 0x37800000, v99
	v_cndmask_b32_e32 v99, v99, v110, vcc
	v_cmp_class_f32_e32 vcc, v95, v228
	v_lshlrev_b32_e32 v110, 16, v96
	v_and_b32_e32 v111, 0xffff0000, v96
	v_cndmask_b32_e32 v95, v99, v95, vcc
	v_div_scale_f32 v116, s[0:1], v95, v95, 1.0
	v_rcp_f32_e32 v117, v116
	v_and_b32_e32 v99, 0xffff0000, v97
	v_fma_f32 v96, -v116, v117, 1.0
	v_fmac_f32_e32 v117, v96, v117
	v_div_scale_f32 v96, vcc, 1.0, v95, 1.0
	v_mul_f32_e32 v97, v96, v117
	v_fma_f32 v122, -v116, v97, v96
	v_fmac_f32_e32 v97, v122, v117
	v_fma_f32 v96, -v116, v97, v96
	v_div_fmas_f32 v96, v96, v117, v97
	v_div_fixup_f32 v95, v96, v95, 1.0
	v_mul_f32_e32 v96, 0x3f4ccccd, v95
	s_waitcnt vmcnt(1)
	v_pk_mul_f32 v[100:101], v[100:101], v[96:97] op_sel_hi:[1,0]
	v_pk_mul_f32 v[102:103], v[102:103], v[96:97] op_sel_hi:[1,0]
	v_pk_mul_f32 v[100:101], v[100:101], v[124:125]
	s_waitcnt vmcnt(0)
	v_pk_mul_f32 v[104:105], v[104:105], v[96:97] op_sel_hi:[1,0]
	v_pk_mul_f32 v[102:103], v[102:103], v[120:121]
	v_pk_mul_f32 v[96:97], v[106:107], v[96:97] op_sel_hi:[1,0]
	v_pk_mul_f32 v[104:105], v[104:105], v[118:119]
	v_pk_mul_f32 v[106:107], v[96:97], v[112:113]
	v_pk_mul_f32 v[96:97], v[100:101], v[110:111]
	v_pk_mul_f32 v[98:99], v[102:103], v[98:99]
	v_cvt_pk_bf16_f32 v96, v96, v97
	v_cvt_pk_bf16_f32 v97, v98, v99
	v_pk_mul_f32 v[98:99], v[104:105], v[108:109]
	v_pk_mul_f32 v[100:101], v[106:107], v[114:115]
	v_cvt_pk_bf16_f32 v98, v98, v99
	v_cvt_pk_bf16_f32 v99, v100, v101
	v_or_b32_e32 v95, 8, v6
	global_store_dwordx4 v[92:93], v[96:99], off offset:1024
	v_or_b32_e32 v92, v202, v95
	v_mov_b32_e32 v93, v203
	v_lshlrev_b64 v[96:97], 10, v[92:93]
	v_lshl_add_u64 v[96:97], s[8:9], 0, v[96:97]
	v_lshl_add_u64 v[96:97], v[96:97], 0, v[218:219]
	v_lshl_add_u64 v[96:97], v[96:97], 0, v[4:5]
	global_load_dwordx4 v[96:99], v[96:97], off
	s_nop 0
	global_load_dwordx4 v[100:103], v7, s[72:73]
	global_load_dwordx4 v[104:107], v7, s[72:73] offset:16
	v_lshl_add_u32 v95, v95, 8, v9
	ds_read_b128 v[108:111], v95
	v_lshlrev_b64 v[92:93], 11, v[92:93]
	v_lshl_add_u64 v[92:93], s[6:7], 0, v[92:93]
	v_lshl_add_u64 v[92:93], v[92:93], 0, v[218:219]
	v_lshl_add_u64 v[92:93], v[92:93], 0, v[4:5]
	s_waitcnt lgkmcnt(0)
	v_lshlrev_b32_e32 v124, 16, v108
	v_and_b32_e32 v125, 0xffff0000, v108
	v_lshlrev_b32_e32 v120, 16, v109
	v_and_b32_e32 v121, 0xffff0000, v109
	v_pk_mul_f32 v[108:109], v[124:125], v[124:125]
	v_pk_mul_f32 v[122:123], v[120:121], v[120:121]
	v_add_f32_e32 v95, v108, v109
	v_lshlrev_b32_e32 v118, 16, v110
	v_and_b32_e32 v119, 0xffff0000, v110
	v_add_f32_e32 v95, v122, v95
	v_lshlrev_b32_e32 v112, 16, v111
	v_and_b32_e32 v113, 0xffff0000, v111
	v_pk_mul_f32 v[110:111], v[118:119], v[118:119]
	v_add_f32_e32 v95, v123, v95
	v_add_f32_e32 v95, v110, v95
	v_pk_mul_f32 v[116:117], v[112:113], v[112:113]
	v_add_f32_e32 v95, v111, v95
	v_add_f32_e32 v95, v116, v95
	v_add_f32_e32 v95, v117, v95
	s_waitcnt vmcnt(2)
	v_lshlrev_b32_e32 v114, 16, v99
	v_add_f32_dpp v95, v95, v95 quad_perm:[1,0,3,2] row_mask:0xf bank_mask:0xf bound_ctrl:1
	v_and_b32_e32 v115, 0xffff0000, v99
	v_lshlrev_b32_e32 v108, 16, v98
	v_add_f32_dpp v95, v95, v95 quad_perm:[2,3,0,1] row_mask:0xf bank_mask:0xf bound_ctrl:1
	v_and_b32_e32 v109, 0xffff0000, v98
	v_lshlrev_b32_e32 v98, 16, v97
	v_add_f32_dpp v95, v95, v95 row_half_mirror row_mask:0xf bank_mask:0xf bound_ctrl:1
	s_nop 1
	v_add_f32_dpp v95, v95, v95 row_mirror row_mask:0xf bank_mask:0xf bound_ctrl:1
	v_fmamk_f32 v95, v95, 0x3c000000, v217
	v_mul_f32_e32 v99, 0x4f800000, v95
	v_cmp_gt_f32_e32 vcc, s56, v95
	s_nop 1
	v_cndmask_b32_e32 v95, v95, v99, vcc
	v_sqrt_f32_e32 v99, v95
	s_nop 0
	v_add_u32_e32 v110, -1, v99
	v_fma_f32 v111, -v110, v99, v95
	v_cmp_ge_f32_e64 s[4:5], 0, v111
	v_add_u32_e32 v111, 1, v99
	s_nop 0
	v_cndmask_b32_e64 v110, v99, v110, s[4:5]
	v_fma_f32 v99, -v111, v99, v95
	v_cmp_lt_f32_e64 s[4:5], 0, v99
	s_nop 1
	v_cndmask_b32_e64 v99, v110, v111, s[4:5]
	v_mul_f32_e32 v110, 0x37800000, v99
	v_cndmask_b32_e32 v99, v99, v110, vcc
	v_cmp_class_f32_e32 vcc, v95, v228
	v_lshlrev_b32_e32 v110, 16, v96
	v_and_b32_e32 v111, 0xffff0000, v96
	v_cndmask_b32_e32 v95, v99, v95, vcc
	v_div_scale_f32 v116, s[0:1], v95, v95, 1.0
	v_rcp_f32_e32 v117, v116
	v_and_b32_e32 v99, 0xffff0000, v97
	v_fma_f32 v96, -v116, v117, 1.0
	v_fmac_f32_e32 v117, v96, v117
	v_div_scale_f32 v96, vcc, 1.0, v95, 1.0
	v_mul_f32_e32 v97, v96, v117
	v_fma_f32 v122, -v116, v97, v96
	v_fmac_f32_e32 v97, v122, v117
	v_fma_f32 v96, -v116, v97, v96
	v_div_fmas_f32 v96, v96, v117, v97
	v_div_fixup_f32 v95, v96, v95, 1.0
	v_mul_f32_e32 v96, 0x3f4ccccd, v95
	s_waitcnt vmcnt(1)
; #define LAS __attribute__((address_space(3)))
; __device__ __forceinline__ unsigned pk2(float lo, float hi) { f32x2_t v = {lo, hi}; bf16x2_t b = __builtin_convertvector(v, bf16x2_t); return __builtin_bit_cast(unsigned, b); }
; template <bool NOMAX>
; __device__ __forceinline__ void diff_unit(const AttnCtx& C, int u, LAS unsigned char* lds) {
;     ...
;         for (int ps = 0; ps < 8; ++ps) {
;             const int rl = ps * 4 + (lanef >> 4); const size_t row = rowb + rl;
;             const v4u sv = *(const LAS v4u*)(stg + rl * 128 + cl * 8);
;             float xv[8];
;             xv[0] = __builtin_bit_cast(float, sv.x << 16); xv[1] = __builtin_bit_cast(float, sv.x & 0xffff0000u); xv[2] = __builtin_bit_cast(float, sv.y << 16); xv[3] = __builtin_bit_cast(float, sv.y & 0xffff0000u);
;             xv[4] = __builtin_bit_cast(float, sv.z << 16); xv[5] = __builtin_bit_cast(float, sv.z & 0xffff0000u); xv[6] = __builtin_bit_cast(float, sv.w << 16); xv[7] = __builtin_bit_cast(float, sv.w & 0xffff0000u);
;             const v4u gv = *(const v4u*)(C.GD + row * 512 + h * 128 + cl * 8);
;             float gg[8];
;             gg[0] = __builtin_bit_cast(float, gv.x << 16); gg[1] = __builtin_bit_cast(float, gv.x & 0xffff0000u); gg[2] = __builtin_bit_cast(float, gv.y << 16); gg[3] = __builtin_bit_cast(float, gv.y & 0xffff0000u);
;             gg[4] = __builtin_bit_cast(float, gv.z << 16); gg[5] = __builtin_bit_cast(float, gv.z & 0xffff0000u); gg[6] = __builtin_bit_cast(float, gv.w << 16); gg[7] = __builtin_bit_cast(float, gv.w & 0xffff0000u);
;             float sq = 0.f;
; #pragma unroll
;             for (int e = 0; e < 8; ++e) sq += xv[e] * xv[e];
;     ...
;             SQDPP(0xB1); SQDPP(0x4E); SQDPP(0x141); SQDPP(0x140);
;     ...
;             const float rs = (1.0f / sqrtf(sq * (1.0f / 128.0f) + EPSN)) * 0.8f;
;             const f32x4 s0 = *(const f32x4*)(C.subln + cl * 8), s1 = *(const f32x4*)(C.subln + cl * 8 + 4);
; #pragma unroll
;             for (int e = 0; e < 4; ++e) { xv[e] *= rs * s0[e]; xv[4 + e] *= rs * s1[e]; }
;             v4u ov; ov.x = pk2(xv[0] * gg[0], xv[1] * gg[1]); ov.y = pk2(xv[2] * gg[2], xv[3] * gg[3]); ov.z = pk2(xv[4] * gg[4], xv[5] * gg[5]); ov.w = pk2(xv[6] * gg[6], xv[7] * gg[7]);
;             *(v4u*)(C.MIX + row * 1024 + 512 + h * 128 + cl * 8) = ov;
	v_pk_mul_f32 v[100:101], v[100:101], v[96:97] op_sel_hi:[1,0]
	v_pk_mul_f32 v[102:103], v[102:103], v[96:97] op_sel_hi:[1,0]
	v_pk_mul_f32 v[100:101], v[100:101], v[124:125]
	s_waitcnt vmcnt(0)
	v_pk_mul_f32 v[104:105], v[104:105], v[96:97] op_sel_hi:[1,0]
	v_pk_mul_f32 v[102:103], v[102:103], v[120:121]
	v_pk_mul_f32 v[96:97], v[106:107], v[96:97] op_sel_hi:[1,0]
	v_pk_mul_f32 v[104:105], v[104:105], v[118:119]
	v_pk_mul_f32 v[106:107], v[96:97], v[112:113]
	v_pk_mul_f32 v[96:97], v[100:101], v[110:111]
	v_pk_mul_f32 v[98:99], v[102:103], v[98:99]
	v_cvt_pk_bf16_f32 v96, v96, v97
	v_cvt_pk_bf16_f32 v97, v98, v99
	v_pk_mul_f32 v[98:99], v[104:105], v[108:109]
	v_pk_mul_f32 v[100:101], v[106:107], v[114:115]
	v_cvt_pk_bf16_f32 v98, v98, v99
	v_cvt_pk_bf16_f32 v99, v100, v101
	v_or_b32_e32 v95, 12, v6
	global_store_dwordx4 v[92:93], v[96:99], off offset:1024
	v_or_b32_e32 v92, v202, v95
	v_mov_b32_e32 v93, v203
	v_lshlrev_b64 v[96:97], 10, v[92:93]
	v_lshl_add_u64 v[96:97], s[8:9], 0, v[96:97]
	v_lshl_add_u64 v[96:97], v[96:97], 0, v[218:219]
	v_lshl_add_u64 v[96:97], v[96:97], 0, v[4:5]
	global_load_dwordx4 v[96:99], v[96:97], off
	s_nop 0
	global_load_dwordx4 v[100:103], v7, s[72:73]
	global_load_dwordx4 v[104:107], v7, s[72:73] offset:16
	v_lshl_add_u32 v95, v95, 8, v9
	ds_read_b128 v[108:111], v95
	v_lshlrev_b64 v[92:93], 11, v[92:93]
	v_lshl_add_u64 v[92:93], s[6:7], 0, v[92:93]
	v_lshl_add_u64 v[92:93], v[92:93], 0, v[218:219]
	v_lshl_add_u64 v[92:93], v[92:93], 0, v[4:5]
	s_waitcnt lgkmcnt(0)
	v_lshlrev_b32_e32 v124, 16, v108
	v_and_b32_e32 v125, 0xffff0000, v108
	v_lshlrev_b32_e32 v120, 16, v109
	v_and_b32_e32 v121, 0xffff0000, v109
	v_pk_mul_f32 v[108:109], v[124:125], v[124:125]
	v_pk_mul_f32 v[122:123], v[120:121], v[120:121]
	v_add_f32_e32 v95, v108, v109
	v_lshlrev_b32_e32 v118, 16, v110
	v_and_b32_e32 v119, 0xffff0000, v110
	v_add_f32_e32 v95, v122, v95
	v_lshlrev_b32_e32 v112, 16, v111
	v_and_b32_e32 v113, 0xffff0000, v111
	v_pk_mul_f32 v[110:111], v[118:119], v[118:119]
	v_add_f32_e32 v95, v123, v95
	v_add_f32_e32 v95, v110, v95
	v_pk_mul_f32 v[116:117], v[112:113], v[112:113]
	v_add_f32_e32 v95, v111, v95
	v_add_f32_e32 v95, v116, v95
	v_add_f32_e32 v95, v117, v95
	s_waitcnt vmcnt(2)
	v_lshlrev_b32_e32 v114, 16, v99
	v_add_f32_dpp v95, v95, v95 quad_perm:[1,0,3,2] row_mask:0xf bank_mask:0xf bound_ctrl:1
	v_and_b32_e32 v115, 0xffff0000, v99
	v_lshlrev_b32_e32 v108, 16, v98
	v_add_f32_dpp v95, v95, v95 quad_perm:[2,3,0,1] row_mask:0xf bank_mask:0xf bound_ctrl:1
	v_and_b32_e32 v109, 0xffff0000, v98
	v_lshlrev_b32_e32 v98, 16, v97
	v_add_f32_dpp v95, v95, v95 row_half_mirror row_mask:0xf bank_mask:0xf bound_ctrl:1
	s_nop 1
	v_add_f32_dpp v95, v95, v95 row_mirror row_mask:0xf bank_mask:0xf bound_ctrl:1
	v_fmamk_f32 v95, v95, 0x3c000000, v217
	v_mul_f32_e32 v99, 0x4f800000, v95
	v_cmp_gt_f32_e32 vcc, s56, v95
	s_nop 1
	v_cndmask_b32_e32 v95, v95, v99, vcc
	v_sqrt_f32_e32 v99, v95
	s_nop 0
	v_add_u32_e32 v110, -1, v99
	v_fma_f32 v111, -v110, v99, v95
	v_cmp_ge_f32_e64 s[4:5], 0, v111
	v_add_u32_e32 v111, 1, v99
	s_nop 0
	v_cndmask_b32_e64 v110, v99, v110, s[4:5]
	v_fma_f32 v99, -v111, v99, v95
	v_cmp_lt_f32_e64 s[4:5], 0, v99
	s_nop 1
	v_cndmask_b32_e64 v99, v110, v111, s[4:5]
	v_mul_f32_e32 v110, 0x37800000, v99
	v_cndmask_b32_e32 v99, v99, v110, vcc
	v_cmp_class_f32_e32 vcc, v95, v228
	v_lshlrev_b32_e32 v110, 16, v96
	v_and_b32_e32 v111, 0xffff0000, v96
	v_cndmask_b32_e32 v95, v99, v95, vcc
	v_div_scale_f32 v116, s[0:1], v95, v95, 1.0
	v_rcp_f32_e32 v117, v116
	v_and_b32_e32 v99, 0xffff0000, v97
	v_fma_f32 v96, -v116, v117, 1.0
	v_fmac_f32_e32 v117, v96, v117
	v_div_scale_f32 v96, vcc, 1.0, v95, 1.0
	v_mul_f32_e32 v97, v96, v117
	v_fma_f32 v122, -v116, v97, v96
	v_fmac_f32_e32 v97, v122, v117
	v_fma_f32 v96, -v116, v97, v96
	v_div_fmas_f32 v96, v96, v117, v97
	v_div_fixup_f32 v95, v96, v95, 1.0
	v_mul_f32_e32 v96, 0x3f4ccccd, v95
	s_waitcnt vmcnt(1)
	v_pk_mul_f32 v[100:101], v[100:101], v[96:97] op_sel_hi:[1,0]
	v_pk_mul_f32 v[102:103], v[102:103], v[96:97] op_sel_hi:[1,0]
	v_pk_mul_f32 v[100:101], v[100:101], v[124:125]
	s_waitcnt vmcnt(0)
	v_pk_mul_f32 v[104:105], v[104:105], v[96:97] op_sel_hi:[1,0]
	v_pk_mul_f32 v[102:103], v[102:103], v[120:121]
	v_pk_mul_f32 v[96:97], v[106:107], v[96:97] op_sel_hi:[1,0]
	v_pk_mul_f32 v[104:105], v[104:105], v[118:119]
	v_pk_mul_f32 v[106:107], v[96:97], v[112:113]
	v_pk_mul_f32 v[96:97], v[100:101], v[110:111]
	v_pk_mul_f32 v[98:99], v[102:103], v[98:99]
	v_cvt_pk_bf16_f32 v96, v96, v97
	v_cvt_pk_bf16_f32 v97, v98, v99
	v_pk_mul_f32 v[98:99], v[104:105], v[108:109]
	v_pk_mul_f32 v[100:101], v[106:107], v[114:115]
	v_cvt_pk_bf16_f32 v98, v98, v99
	v_cvt_pk_bf16_f32 v99, v100, v101
	v_or_b32_e32 v95, 16, v6
	global_store_dwordx4 v[92:93], v[96:99], off offset:1024
	v_or_b32_e32 v92, v202, v95
	v_mov_b32_e32 v93, v203
	v_lshlrev_b64 v[96:97], 10, v[92:93]
	v_lshl_add_u64 v[96:97], s[8:9], 0, v[96:97]
	v_lshl_add_u64 v[96:97], v[96:97], 0, v[218:219]
	v_lshl_add_u64 v[96:97], v[96:97], 0, v[4:5]
	global_load_dwordx4 v[96:99], v[96:97], off
	s_nop 0
	global_load_dwordx4 v[100:103], v7, s[72:73]
	global_load_dwordx4 v[104:107], v7, s[72:73] offset:16
	v_lshl_add_u32 v95, v95, 8, v9
	ds_read_b128 v[108:111], v95
	v_lshlrev_b64 v[92:93], 11, v[92:93]
	v_lshl_add_u64 v[92:93], s[6:7], 0, v[92:93]
	v_lshl_add_u64 v[92:93], v[92:93], 0, v[218:219]
	v_lshl_add_u64 v[92:93], v[92:93], 0, v[4:5]
	s_waitcnt lgkmcnt(0)
; #define LAS __attribute__((address_space(3)))
; __device__ __forceinline__ unsigned pk2(float lo, float hi) { f32x2_t v = {lo, hi}; bf16x2_t b = __builtin_convertvector(v, bf16x2_t); return __builtin_bit_cast(unsigned, b); }
; template <bool NOMAX>
; __device__ __forceinline__ void diff_unit(const AttnCtx& C, int u, LAS unsigned char* lds) {
;     ...
;         for (int ps = 0; ps < 8; ++ps) {
;             const int rl = ps * 4 + (lanef >> 4); const size_t row = rowb + rl;
;             const v4u sv = *(const LAS v4u*)(stg + rl * 128 + cl * 8);
;             float xv[8];
;             xv[0] = __builtin_bit_cast(float, sv.x << 16); xv[1] = __builtin_bit_cast(float, sv.x & 0xffff0000u); xv[2] = __builtin_bit_cast(float, sv.y << 16); xv[3] = __builtin_bit_cast(float, sv.y & 0xffff0000u);
;             xv[4] = __builtin_bit_cast(float, sv.z << 16); xv[5] = __builtin_bit_cast(float, sv.z & 0xffff0000u); xv[6] = __builtin_bit_cast(float, sv.w << 16); xv[7] = __builtin_bit_cast(float, sv.w & 0xffff0000u);
;             const v4u gv = *(const v4u*)(C.GD + row * 512 + h * 128 + cl * 8);
;             float gg[8];
;             gg[0] = __builtin_bit_cast(float, gv.x << 16); gg[1] = __builtin_bit_cast(float, gv.x & 0xffff0000u); gg[2] = __builtin_bit_cast(float, gv.y << 16); gg[3] = __builtin_bit_cast(float, gv.y & 0xffff0000u);
;             gg[4] = __builtin_bit_cast(float, gv.z << 16); gg[5] = __builtin_bit_cast(float, gv.z & 0xffff0000u); gg[6] = __builtin_bit_cast(float, gv.w << 16); gg[7] = __builtin_bit_cast(float, gv.w & 0xffff0000u);
;             float sq = 0.f;
; #pragma unroll
;             for (int e = 0; e < 8; ++e) sq += xv[e] * xv[e];
;     ...
;             SQDPP(0xB1); SQDPP(0x4E); SQDPP(0x141); SQDPP(0x140);
;     ...
;             const float rs = (1.0f / sqrtf(sq * (1.0f / 128.0f) + EPSN)) * 0.8f;
;             const f32x4 s0 = *(const f32x4*)(C.subln + cl * 8), s1 = *(const f32x4*)(C.subln + cl * 8 + 4);
; #pragma unroll
;             for (int e = 0; e < 4; ++e) { xv[e] *= rs * s0[e]; xv[4 + e] *= rs * s1[e]; }
;             v4u ov; ov.x = pk2(xv[0] * gg[0], xv[1] * gg[1]); ov.y = pk2(xv[2] * gg[2], xv[3] * gg[3]); ov.z = pk2(xv[4] * gg[4], xv[5] * gg[5]); ov.w = pk2(xv[6] * gg[6], xv[7] * gg[7]);
;             *(v4u*)(C.MIX + row * 1024 + 512 + h * 128 + cl * 8) = ov;
	v_lshlrev_b32_e32 v124, 16, v108
	v_and_b32_e32 v125, 0xffff0000, v108
	v_lshlrev_b32_e32 v120, 16, v109
	v_and_b32_e32 v121, 0xffff0000, v109
	v_pk_mul_f32 v[108:109], v[124:125], v[124:125]
	v_pk_mul_f32 v[122:123], v[120:121], v[120:121]
	v_add_f32_e32 v95, v108, v109
	v_lshlrev_b32_e32 v118, 16, v110
	v_and_b32_e32 v119, 0xffff0000, v110
	v_add_f32_e32 v95, v122, v95
	v_lshlrev_b32_e32 v112, 16, v111
	v_and_b32_e32 v113, 0xffff0000, v111
	v_pk_mul_f32 v[110:111], v[118:119], v[118:119]
	v_add_f32_e32 v95, v123, v95
	v_add_f32_e32 v95, v110, v95
	v_pk_mul_f32 v[116:117], v[112:113], v[112:113]
	v_add_f32_e32 v95, v111, v95
	v_add_f32_e32 v95, v116, v95
	v_add_f32_e32 v95, v117, v95
	s_waitcnt vmcnt(2)
	v_lshlrev_b32_e32 v114, 16, v99
	v_add_f32_dpp v95, v95, v95 quad_perm:[1,0,3,2] row_mask:0xf bank_mask:0xf bound_ctrl:1
	v_and_b32_e32 v115, 0xffff0000, v99
	v_lshlrev_b32_e32 v108, 16, v98
	v_add_f32_dpp v95, v95, v95 quad_perm:[2,3,0,1] row_mask:0xf bank_mask:0xf bound_ctrl:1
	v_and_b32_e32 v109, 0xffff0000, v98
	v_lshlrev_b32_e32 v98, 16, v97
	v_add_f32_dpp v95, v95, v95 row_half_mirror row_mask:0xf bank_mask:0xf bound_ctrl:1
	s_nop 1
	v_add_f32_dpp v95, v95, v95 row_mirror row_mask:0xf bank_mask:0xf bound_ctrl:1
	v_fmamk_f32 v95, v95, 0x3c000000, v217
	v_mul_f32_e32 v99, 0x4f800000, v95
	v_cmp_gt_f32_e32 vcc, s56, v95
	s_nop 1
	v_cndmask_b32_e32 v95, v95, v99, vcc
	v_sqrt_f32_e32 v99, v95
	s_nop 0
	v_add_u32_e32 v110, -1, v99
	v_fma_f32 v111, -v110, v99, v95
	v_cmp_ge_f32_e64 s[4:5], 0, v111
	v_add_u32_e32 v111, 1, v99
	s_nop 0
	v_cndmask_b32_e64 v110, v99, v110, s[4:5]
	v_fma_f32 v99, -v111, v99, v95
	v_cmp_lt_f32_e64 s[4:5], 0, v99
	s_nop 1
	v_cndmask_b32_e64 v99, v110, v111, s[4:5]
	v_mul_f32_e32 v110, 0x37800000, v99
	v_cndmask_b32_e32 v99, v99, v110, vcc
	v_cmp_class_f32_e32 vcc, v95, v228
	v_lshlrev_b32_e32 v110, 16, v96
	v_and_b32_e32 v111, 0xffff0000, v96
	v_cndmask_b32_e32 v95, v99, v95, vcc
	v_div_scale_f32 v116, s[0:1], v95, v95, 1.0
	v_rcp_f32_e32 v117, v116
	v_and_b32_e32 v99, 0xffff0000, v97
	v_fma_f32 v96, -v116, v117, 1.0
	v_fmac_f32_e32 v117, v96, v117
	v_div_scale_f32 v96, vcc, 1.0, v95, 1.0
	v_mul_f32_e32 v97, v96, v117
	v_fma_f32 v122, -v116, v97, v96
	v_fmac_f32_e32 v97, v122, v117
	v_fma_f32 v96, -v116, v97, v96
	v_div_fmas_f32 v96, v96, v117, v97
	v_div_fixup_f32 v95, v96, v95, 1.0
	v_mul_f32_e32 v96, 0x3f4ccccd, v95
	s_waitcnt vmcnt(1)
	v_pk_mul_f32 v[100:101], v[100:101], v[96:97] op_sel_hi:[1,0]
	v_pk_mul_f32 v[102:103], v[102:103], v[96:97] op_sel_hi:[1,0]
	v_pk_mul_f32 v[100:101], v[100:101], v[124:125]
	s_waitcnt vmcnt(0)
	v_pk_mul_f32 v[104:105], v[104:105], v[96:97] op_sel_hi:[1,0]
	v_pk_mul_f32 v[102:103], v[102:103], v[120:121]
	v_pk_mul_f32 v[96:97], v[106:107], v[96:97] op_sel_hi:[1,0]
	v_pk_mul_f32 v[104:105], v[104:105], v[118:119]
	v_pk_mul_f32 v[106:107], v[96:97], v[112:113]
	v_pk_mul_f32 v[96:97], v[100:101], v[110:111]
	v_pk_mul_f32 v[98:99], v[102:103], v[98:99]
	v_cvt_pk_bf16_f32 v96, v96, v97
	v_cvt_pk_bf16_f32 v97, v98, v99
	v_pk_mul_f32 v[98:99], v[104:105], v[108:109]
	v_pk_mul_f32 v[100:101], v[106:107], v[114:115]
	v_cvt_pk_bf16_f32 v98, v98, v99
	v_cvt_pk_bf16_f32 v99, v100, v101
	v_or_b32_e32 v95, 20, v6
	global_store_dwordx4 v[92:93], v[96:99], off offset:1024
	v_or_b32_e32 v92, v202, v95
	v_mov_b32_e32 v93, v203
	v_lshlrev_b64 v[96:97], 10, v[92:93]
	v_lshl_add_u64 v[96:97], s[8:9], 0, v[96:97]
	v_lshl_add_u64 v[96:97], v[96:97], 0, v[218:219]
	v_lshl_add_u64 v[96:97], v[96:97], 0, v[4:5]
	global_load_dwordx4 v[96:99], v[96:97], off
	s_nop 0
	global_load_dwordx4 v[100:103], v7, s[72:73]
	global_load_dwordx4 v[104:107], v7, s[72:73] offset:16
	v_lshl_add_u32 v95, v95, 8, v9
	ds_read_b128 v[108:111], v95
	v_lshlrev_b64 v[92:93], 11, v[92:93]
	v_lshl_add_u64 v[92:93], s[6:7], 0, v[92:93]
	v_lshl_add_u64 v[92:93], v[92:93], 0, v[218:219]
	v_lshl_add_u64 v[92:93], v[92:93], 0, v[4:5]
	s_waitcnt lgkmcnt(0)
	v_lshlrev_b32_e32 v124, 16, v108
	v_and_b32_e32 v125, 0xffff0000, v108
	v_lshlrev_b32_e32 v120, 16, v109
	v_and_b32_e32 v121, 0xffff0000, v109
	v_pk_mul_f32 v[108:109], v[124:125], v[124:125]
	v_pk_mul_f32 v[122:123], v[120:121], v[120:121]
	v_add_f32_e32 v95, v108, v109
	v_lshlrev_b32_e32 v118, 16, v110
	v_and_b32_e32 v119, 0xffff0000, v110
	v_add_f32_e32 v95, v122, v95
	v_lshlrev_b32_e32 v112, 16, v111
	v_and_b32_e32 v113, 0xffff0000, v111
	v_pk_mul_f32 v[110:111], v[118:119], v[118:119]
	v_add_f32_e32 v95, v123, v95
	v_add_f32_e32 v95, v110, v95
	v_pk_mul_f32 v[116:117], v[112:113], v[112:113]
	v_add_f32_e32 v95, v111, v95
	v_add_f32_e32 v95, v116, v95
	v_add_f32_e32 v95, v117, v95
	s_waitcnt vmcnt(2)
	v_lshlrev_b32_e32 v114, 16, v99
	v_add_f32_dpp v95, v95, v95 quad_perm:[1,0,3,2] row_mask:0xf bank_mask:0xf bound_ctrl:1
	v_and_b32_e32 v115, 0xffff0000, v99
	v_lshlrev_b32_e32 v108, 16, v98
	v_add_f32_dpp v95, v95, v95 quad_perm:[2,3,0,1] row_mask:0xf bank_mask:0xf bound_ctrl:1
	v_and_b32_e32 v109, 0xffff0000, v98
	v_lshlrev_b32_e32 v98, 16, v97
	v_add_f32_dpp v95, v95, v95 row_half_mirror row_mask:0xf bank_mask:0xf bound_ctrl:1
	s_nop 1
	v_add_f32_dpp v95, v95, v95 row_mirror row_mask:0xf bank_mask:0xf bound_ctrl:1
	v_fmamk_f32 v95, v95, 0x3c000000, v217
	v_mul_f32_e32 v99, 0x4f800000, v95
	v_cmp_gt_f32_e32 vcc, s56, v95
	s_nop 1
	v_cndmask_b32_e32 v95, v95, v99, vcc
	v_sqrt_f32_e32 v99, v95
	s_nop 0
	v_add_u32_e32 v110, -1, v99
	v_fma_f32 v111, -v110, v99, v95
	v_cmp_ge_f32_e64 s[4:5], 0, v111
	v_add_u32_e32 v111, 1, v99
	s_nop 0
	v_cndmask_b32_e64 v110, v99, v110, s[4:5]
	v_fma_f32 v99, -v111, v99, v95
	v_cmp_lt_f32_e64 s[4:5], 0, v99
	s_nop 1
	v_cndmask_b32_e64 v99, v110, v111, s[4:5]
	v_mul_f32_e32 v110, 0x37800000, v99
	v_cndmask_b32_e32 v99, v99, v110, vcc
	v_cmp_class_f32_e32 vcc, v95, v228
	v_lshlrev_b32_e32 v110, 16, v96
	v_and_b32_e32 v111, 0xffff0000, v96
	v_cndmask_b32_e32 v95, v99, v95, vcc
	v_div_scale_f32 v116, s[0:1], v95, v95, 1.0
	v_rcp_f32_e32 v117, v116
	v_and_b32_e32 v99, 0xffff0000, v97
	v_fma_f32 v96, -v116, v117, 1.0
	v_fmac_f32_e32 v117, v96, v117
	v_div_scale_f32 v96, vcc, 1.0, v95, 1.0
	v_mul_f32_e32 v97, v96, v117
	v_fma_f32 v122, -v116, v97, v96
	v_fmac_f32_e32 v97, v122, v117
	v_fma_f32 v96, -v116, v97, v96
	v_div_fmas_f32 v96, v96, v117, v97
	v_div_fixup_f32 v95, v96, v95, 1.0
	v_mul_f32_e32 v96, 0x3f4ccccd, v95
	s_waitcnt vmcnt(1)
; #define LAS __attribute__((address_space(3)))
; __device__ __forceinline__ unsigned pk2(float lo, float hi) { f32x2_t v = {lo, hi}; bf16x2_t b = __builtin_convertvector(v, bf16x2_t); return __builtin_bit_cast(unsigned, b); }
; template <bool NOMAX>
; __device__ __forceinline__ void diff_unit(const AttnCtx& C, int u, LAS unsigned char* lds) {
;     ...
;         for (int ps = 0; ps < 8; ++ps) {
;             const int rl = ps * 4 + (lanef >> 4); const size_t row = rowb + rl;
;             const v4u sv = *(const LAS v4u*)(stg + rl * 128 + cl * 8);
;             float xv[8];
;             xv[0] = __builtin_bit_cast(float, sv.x << 16); xv[1] = __builtin_bit_cast(float, sv.x & 0xffff0000u); xv[2] = __builtin_bit_cast(float, sv.y << 16); xv[3] = __builtin_bit_cast(float, sv.y & 0xffff0000u);
;             xv[4] = __builtin_bit_cast(float, sv.z << 16); xv[5] = __builtin_bit_cast(float, sv.z & 0xffff0000u); xv[6] = __builtin_bit_cast(float, sv.w << 16); xv[7] = __builtin_bit_cast(float, sv.w & 0xffff0000u);
;             const v4u gv = *(const v4u*)(C.GD + row * 512 + h * 128 + cl * 8);
;             float gg[8];
;             gg[0] = __builtin_bit_cast(float, gv.x << 16); gg[1] = __builtin_bit_cast(float, gv.x & 0xffff0000u); gg[2] = __builtin_bit_cast(float, gv.y << 16); gg[3] = __builtin_bit_cast(float, gv.y & 0xffff0000u);
;             gg[4] = __builtin_bit_cast(float, gv.z << 16); gg[5] = __builtin_bit_cast(float, gv.z & 0xffff0000u); gg[6] = __builtin_bit_cast(float, gv.w << 16); gg[7] = __builtin_bit_cast(float, gv.w & 0xffff0000u);
;             float sq = 0.f;
; #pragma unroll
;             for (int e = 0; e < 8; ++e) sq += xv[e] * xv[e];
;     ...
;             SQDPP(0xB1); SQDPP(0x4E); SQDPP(0x141); SQDPP(0x140);
;     ...
;             const float rs = (1.0f / sqrtf(sq * (1.0f / 128.0f) + EPSN)) * 0.8f;
;             const f32x4 s0 = *(const f32x4*)(C.subln + cl * 8), s1 = *(const f32x4*)(C.subln + cl * 8 + 4);
; #pragma unroll
;             for (int e = 0; e < 4; ++e) { xv[e] *= rs * s0[e]; xv[4 + e] *= rs * s1[e]; }
;             v4u ov; ov.x = pk2(xv[0] * gg[0], xv[1] * gg[1]); ov.y = pk2(xv[2] * gg[2], xv[3] * gg[3]); ov.z = pk2(xv[4] * gg[4], xv[5] * gg[5]); ov.w = pk2(xv[6] * gg[6], xv[7] * gg[7]);
;             *(v4u*)(C.MIX + row * 1024 + 512 + h * 128 + cl * 8) = ov;
	v_pk_mul_f32 v[100:101], v[100:101], v[96:97] op_sel_hi:[1,0]
	v_pk_mul_f32 v[102:103], v[102:103], v[96:97] op_sel_hi:[1,0]
	v_pk_mul_f32 v[100:101], v[100:101], v[124:125]
	s_waitcnt vmcnt(0)
	v_pk_mul_f32 v[104:105], v[104:105], v[96:97] op_sel_hi:[1,0]
	v_pk_mul_f32 v[102:103], v[102:103], v[120:121]
	v_pk_mul_f32 v[96:97], v[106:107], v[96:97] op_sel_hi:[1,0]
	v_pk_mul_f32 v[104:105], v[104:105], v[118:119]
	v_pk_mul_f32 v[106:107], v[96:97], v[112:113]
	v_pk_mul_f32 v[96:97], v[100:101], v[110:111]
	v_pk_mul_f32 v[98:99], v[102:103], v[98:99]
	v_cvt_pk_bf16_f32 v96, v96, v97
	v_cvt_pk_bf16_f32 v97, v98, v99
	v_pk_mul_f32 v[98:99], v[104:105], v[108:109]
	v_pk_mul_f32 v[100:101], v[106:107], v[114:115]
	v_cvt_pk_bf16_f32 v98, v98, v99
	v_cvt_pk_bf16_f32 v99, v100, v101
	v_or_b32_e32 v95, 24, v6
	global_store_dwordx4 v[92:93], v[96:99], off offset:1024
	v_or_b32_e32 v92, v202, v95
	v_mov_b32_e32 v93, v203
	v_lshlrev_b64 v[96:97], 10, v[92:93]
	v_lshl_add_u64 v[96:97], s[8:9], 0, v[96:97]
	v_lshl_add_u64 v[96:97], v[96:97], 0, v[218:219]
	v_lshl_add_u64 v[96:97], v[96:97], 0, v[4:5]
	global_load_dwordx4 v[96:99], v[96:97], off
	s_nop 0
	global_load_dwordx4 v[100:103], v7, s[72:73]
	global_load_dwordx4 v[104:107], v7, s[72:73] offset:16
	v_lshl_add_u32 v95, v95, 8, v9
	ds_read_b128 v[108:111], v95
	v_lshlrev_b64 v[92:93], 11, v[92:93]
	v_lshl_add_u64 v[92:93], s[6:7], 0, v[92:93]
	v_lshl_add_u64 v[92:93], v[92:93], 0, v[218:219]
	v_or_b32_e32 v6, 28, v6
	s_waitcnt lgkmcnt(0)
	v_lshlrev_b32_e32 v124, 16, v108
	v_and_b32_e32 v125, 0xffff0000, v108
	v_lshlrev_b32_e32 v120, 16, v109
	v_and_b32_e32 v121, 0xffff0000, v109
	v_pk_mul_f32 v[108:109], v[124:125], v[124:125]
	v_pk_mul_f32 v[122:123], v[120:121], v[120:121]
	v_add_f32_e32 v95, v108, v109
	v_lshlrev_b32_e32 v118, 16, v110
	v_and_b32_e32 v119, 0xffff0000, v110
	v_add_f32_e32 v95, v122, v95
	v_lshlrev_b32_e32 v112, 16, v111
	v_and_b32_e32 v113, 0xffff0000, v111
	v_pk_mul_f32 v[110:111], v[118:119], v[118:119]
	v_add_f32_e32 v95, v123, v95
	v_add_f32_e32 v95, v110, v95
	v_pk_mul_f32 v[116:117], v[112:113], v[112:113]
	v_add_f32_e32 v95, v111, v95
	v_add_f32_e32 v95, v116, v95
	v_add_f32_e32 v95, v117, v95
	v_lshl_add_u64 v[92:93], v[92:93], 0, v[4:5]
	v_or_b32_e32 v202, v202, v6
	v_add_f32_dpp v95, v95, v95 quad_perm:[1,0,3,2] row_mask:0xf bank_mask:0xf bound_ctrl:1
	v_lshl_add_u32 v6, v6, 8, v9
	s_waitcnt vmcnt(2)
	v_lshlrev_b32_e32 v114, 16, v99
	v_add_f32_dpp v95, v95, v95 quad_perm:[2,3,0,1] row_mask:0xf bank_mask:0xf bound_ctrl:1
	v_and_b32_e32 v115, 0xffff0000, v99
	v_lshlrev_b32_e32 v108, 16, v98
	v_add_f32_dpp v95, v95, v95 row_half_mirror row_mask:0xf bank_mask:0xf bound_ctrl:1
	v_and_b32_e32 v109, 0xffff0000, v98
	v_lshlrev_b32_e32 v98, 16, v97
	v_add_f32_dpp v95, v95, v95 row_mirror row_mask:0xf bank_mask:0xf bound_ctrl:1
	v_fmamk_f32 v95, v95, 0x3c000000, v217
	v_mul_f32_e32 v99, 0x4f800000, v95
	v_cmp_gt_f32_e32 vcc, s56, v95
	s_nop 1
	v_cndmask_b32_e32 v95, v95, v99, vcc
	v_sqrt_f32_e32 v99, v95
	s_nop 0
	v_add_u32_e32 v110, -1, v99
	v_fma_f32 v111, -v110, v99, v95
	v_cmp_ge_f32_e64 s[4:5], 0, v111
	v_add_u32_e32 v111, 1, v99
	s_nop 0
	v_cndmask_b32_e64 v110, v99, v110, s[4:5]
	v_fma_f32 v99, -v111, v99, v95
	v_cmp_lt_f32_e64 s[4:5], 0, v99
	s_nop 1
	v_cndmask_b32_e64 v99, v110, v111, s[4:5]
	v_mul_f32_e32 v110, 0x37800000, v99
	v_cndmask_b32_e32 v99, v99, v110, vcc
	v_cmp_class_f32_e32 vcc, v95, v228
	v_lshlrev_b32_e32 v110, 16, v96
	v_and_b32_e32 v111, 0xffff0000, v96
	v_cndmask_b32_e32 v95, v99, v95, vcc
	v_div_scale_f32 v116, s[0:1], v95, v95, 1.0
	v_rcp_f32_e32 v117, v116
	v_and_b32_e32 v99, 0xffff0000, v97
	v_fma_f32 v96, -v116, v117, 1.0
	v_fmac_f32_e32 v117, v96, v117
	v_div_scale_f32 v96, vcc, 1.0, v95, 1.0
	v_mul_f32_e32 v97, v96, v117
	v_fma_f32 v122, -v116, v97, v96
	v_fmac_f32_e32 v97, v122, v117
	v_fma_f32 v96, -v116, v97, v96
	v_div_fmas_f32 v96, v96, v117, v97
	v_div_fixup_f32 v95, v96, v95, 1.0
	v_mul_f32_e32 v96, 0x3f4ccccd, v95
	s_waitcnt vmcnt(1)
	v_pk_mul_f32 v[100:101], v[100:101], v[96:97] op_sel_hi:[1,0]
	v_pk_mul_f32 v[102:103], v[102:103], v[96:97] op_sel_hi:[1,0]
	v_pk_mul_f32 v[100:101], v[100:101], v[124:125]
	s_waitcnt vmcnt(0)
	v_pk_mul_f32 v[104:105], v[104:105], v[96:97] op_sel_hi:[1,0]
	v_pk_mul_f32 v[102:103], v[102:103], v[120:121]
	v_pk_mul_f32 v[96:97], v[106:107], v[96:97] op_sel_hi:[1,0]
	v_pk_mul_f32 v[104:105], v[104:105], v[118:119]
	v_pk_mul_f32 v[106:107], v[96:97], v[112:113]
	v_pk_mul_f32 v[96:97], v[100:101], v[110:111]
	v_pk_mul_f32 v[98:99], v[102:103], v[98:99]
	v_cvt_pk_bf16_f32 v96, v96, v97
	v_cvt_pk_bf16_f32 v97, v98, v99
	v_pk_mul_f32 v[98:99], v[104:105], v[108:109]
	v_pk_mul_f32 v[100:101], v[106:107], v[114:115]
	v_cvt_pk_bf16_f32 v98, v98, v99
	v_cvt_pk_bf16_f32 v99, v100, v101
	global_store_dwordx4 v[92:93], v[96:99], off offset:1024
	v_lshlrev_b64 v[92:93], 10, v[202:203]
	v_lshl_add_u64 v[92:93], s[8:9], 0, v[92:93]
	v_lshl_add_u64 v[92:93], v[92:93], 0, v[218:219]
	v_lshl_add_u64 v[92:93], v[92:93], 0, v[4:5]
	global_load_dwordx4 v[96:99], v[92:93], off
	global_load_dwordx4 v[100:103], v7, s[72:73]
	global_load_dwordx4 v[104:107], v7, s[72:73] offset:16
	ds_read_b128 v[108:111], v6
	s_waitcnt lgkmcnt(0)
	v_lshlrev_b32_e32 v120, 16, v108
	v_and_b32_e32 v121, 0xffff0000, v108
	v_lshlrev_b32_e32 v116, 16, v109
	v_and_b32_e32 v117, 0xffff0000, v109
	v_pk_mul_f32 v[108:109], v[120:121], v[120:121]
	v_pk_mul_f32 v[118:119], v[116:117], v[116:117]
	v_add_f32_e32 v9, v108, v109
	v_lshlrev_b32_e32 v114, 16, v110
	v_and_b32_e32 v115, 0xffff0000, v110
	v_add_f32_e32 v9, v118, v9
	v_lshlrev_b32_e32 v6, 16, v111
	v_and_b32_e32 v7, 0xffff0000, v111
	v_pk_mul_f32 v[110:111], v[114:115], v[114:115]
	v_add_f32_e32 v9, v119, v9
	v_add_f32_e32 v9, v110, v9
	v_pk_mul_f32 v[112:113], v[6:7], v[6:7]
	v_add_f32_e32 v9, v111, v9
	v_add_f32_e32 v9, v112, v9
	v_add_f32_e32 v9, v113, v9
	s_waitcnt vmcnt(2)
; __device__ __forceinline__ unsigned pk2(float lo, float hi) { f32x2_t v = {lo, hi}; bf16x2_t b = __builtin_convertvector(v, bf16x2_t); return __builtin_bit_cast(unsigned, b); }
; template <bool NOMAX>
; __device__ __forceinline__ void diff_unit(const AttnCtx& C, int u, LAS unsigned char* lds) {
;     ...
;     if (umap == 0) {
;         f32x4* st = (f32x4*)(C.stash + (slot * 512 + tidf) * 64);
; #pragma unroll
;         for (int d = 0; d < 4; ++d)
; #pragma unroll
;             for (int gq = 0; gq < 4; ++gq) st[d * 4 + gq] = (f32x4){o[d][4 * gq] * rli[4 * gq], o[d][4 * gq + 1] * rli[4 * gq + 1], o[d][4 * gq + 2] * rli[4 * gq + 2], o[d][4 * gq + 3] * rli[4 * gq + 3]};
;         asm volatile("s_waitcnt vmcnt(0)" ::: "memory");
;         __syncthreads();
;         if (tidf == 0) { __builtin_amdgcn_fence(__ATOMIC_RELEASE, "agent"); asm volatile("s_waitcnt vmcnt(0)" ::: "memory");
;             __hip_atomic_store(C.flags + 16 * (qb * 4 + h), 1u, __ATOMIC_RELAXED, __HIP_MEMORY_SCOPE_AGENT); }
;     ...
;             const float rs = (1.0f / sqrtf(sq * (1.0f / 128.0f) + EPSN)) * 0.8f;
;             const f32x4 s0 = *(const f32x4*)(C.subln + cl * 8), s1 = *(const f32x4*)(C.subln + cl * 8 + 4);
; #pragma unroll
;             for (int e = 0; e < 4; ++e) { xv[e] *= rs * s0[e]; xv[4 + e] *= rs * s1[e]; }
;             v4u ov; ov.x = pk2(xv[0] * gg[0], xv[1] * gg[1]); ov.y = pk2(xv[2] * gg[2], xv[3] * gg[3]); ov.z = pk2(xv[4] * gg[4], xv[5] * gg[5]); ov.w = pk2(xv[6] * gg[6], xv[7] * gg[7]);
;             *(v4u*)(C.MIX + row * 1024 + 512 + h * 128 + cl * 8) = ov;
	v_lshlrev_b32_e32 v92, 16, v99
	v_add_f32_dpp v9, v9, v9 quad_perm:[1,0,3,2] row_mask:0xf bank_mask:0xf bound_ctrl:1
	v_and_b32_e32 v93, 0xffff0000, v99
	v_and_b32_e32 v111, 0xffff0000, v96
	v_add_f32_dpp v9, v9, v9 quad_perm:[2,3,0,1] row_mask:0xf bank_mask:0xf bound_ctrl:1
	v_lshlrev_b32_e32 v108, 16, v98
	v_and_b32_e32 v109, 0xffff0000, v98
	v_add_f32_dpp v9, v9, v9 row_half_mirror row_mask:0xf bank_mask:0xf bound_ctrl:1
	v_lshlrev_b32_e32 v98, 16, v97
	s_nop 0
	v_add_f32_dpp v9, v9, v9 row_mirror row_mask:0xf bank_mask:0xf bound_ctrl:1
	v_fmamk_f32 v9, v9, 0x3c000000, v217
	v_mul_f32_e32 v95, 0x4f800000, v9
	v_cmp_gt_f32_e32 vcc, s56, v9
	s_nop 1
	v_cndmask_b32_e32 v9, v9, v95, vcc
	v_sqrt_f32_e32 v95, v9
	s_nop 0
	v_add_u32_e32 v99, -1, v95
	v_fma_f32 v110, -v99, v95, v9
	v_cmp_ge_f32_e64 s[4:5], 0, v110
	v_add_u32_e32 v110, 1, v95
	s_nop 0
	v_cndmask_b32_e64 v99, v95, v99, s[4:5]
	v_fma_f32 v95, -v110, v95, v9
	v_cmp_lt_f32_e64 s[4:5], 0, v95
	s_nop 1
	v_cndmask_b32_e64 v95, v99, v110, s[4:5]
	v_mul_f32_e32 v99, 0x37800000, v95
	v_cndmask_b32_e32 v95, v95, v99, vcc
	v_cmp_class_f32_e32 vcc, v9, v228
	v_lshlrev_b32_e32 v110, 16, v96
	v_and_b32_e32 v99, 0xffff0000, v97
	v_cndmask_b32_e32 v9, v95, v9, vcc
	v_div_scale_f32 v95, s[0:1], v9, v9, 1.0
	v_rcp_f32_e32 v112, v95
	s_nop 0
	v_fma_f32 v96, -v95, v112, 1.0
	v_fmac_f32_e32 v112, v96, v112
	v_div_scale_f32 v96, vcc, 1.0, v9, 1.0
	v_mul_f32_e32 v97, v96, v112
	v_fma_f32 v113, -v95, v97, v96
	v_fmac_f32_e32 v97, v113, v112
	v_fma_f32 v95, -v95, v97, v96
	v_div_fmas_f32 v95, v95, v112, v97
	v_div_fixup_f32 v9, v95, v9, 1.0
	v_mul_f32_e32 v96, 0x3f4ccccd, v9
	s_waitcnt vmcnt(1)
	v_pk_mul_f32 v[100:101], v[100:101], v[96:97] op_sel_hi:[1,0]
	v_pk_mul_f32 v[102:103], v[102:103], v[96:97] op_sel_hi:[1,0]
	v_pk_mul_f32 v[100:101], v[100:101], v[120:121]
	s_waitcnt vmcnt(0)
	v_pk_mul_f32 v[104:105], v[104:105], v[96:97] op_sel_hi:[1,0]
	v_pk_mul_f32 v[102:103], v[102:103], v[116:117]
	v_pk_mul_f32 v[96:97], v[106:107], v[96:97] op_sel_hi:[1,0]
	v_pk_mul_f32 v[104:105], v[104:105], v[114:115]
	v_pk_mul_f32 v[6:7], v[96:97], v[6:7]
	v_pk_mul_f32 v[96:97], v[100:101], v[110:111]
	v_pk_mul_f32 v[98:99], v[102:103], v[98:99]
	v_cvt_pk_bf16_f32 v96, v96, v97
	v_cvt_pk_bf16_f32 v97, v98, v99
	v_pk_mul_f32 v[98:99], v[104:105], v[108:109]
	v_pk_mul_f32 v[6:7], v[6:7], v[92:93]
	v_cvt_pk_bf16_f32 v98, v98, v99
	v_cvt_pk_bf16_f32 v99, v6, v7
	v_lshlrev_b64 v[6:7], 11, v[202:203]
	v_lshl_add_u64 v[6:7], s[6:7], 0, v[6:7]
	v_lshl_add_u64 v[6:7], v[6:7], 0, v[218:219]
	v_lshl_add_u64 v[4:5], v[6:7], 0, v[4:5]
	s_mov_b64 s[6:7], 0
	global_store_dwordx4 v[4:5], v[96:99], off offset:1024
.LBB0_533:
	s_and_b64 vcc, exec, s[6:7]
	s_cbranch_vccz .LBB0_537
	v_ashrrev_i32_e32 v9, 31, v8
	v_lshlrev_b64 v[4:5], 17, v[2:3]
	v_lshl_add_u64 v[4:5], s[12:13], 0, v[4:5]
	v_and_b32_e32 v6, 63, v8
	v_lshrrev_b32_e32 v7, 6, v8
	v_lshlrev_b32_e32 v6, 4, v6
	v_lshl_add_u32 v6, v7, 14, v6
	v_add_u32_e32 v6, 0x1000, v6
	v_mov_b32_e32 v7, 0
	s_mov_b64 s[98:99], 0x2000
	v_lshl_add_u64 v[92:93], v[4:5], 0, v[6:7]
	v_lshl_add_u64 v[254:255], v[92:93], 0, s[98:99]
	v_pk_mul_f32 v[4:5], v[68:69], v[90:91]
	v_pk_mul_f32 v[6:7], v[70:71], v[88:89]
	global_store_dwordx4 v[92:93], v[4:7], off offset:-4096
	v_cmp_eq_u32_e32 vcc, 0, v8
	s_nop 0
	v_pk_mul_f32 v[4:5], v[72:73], v[14:15]
	v_pk_mul_f32 v[6:7], v[74:75], v[86:87]
	global_store_dwordx4 v[92:93], v[4:7], off offset:-3072
	s_nop 1
	v_pk_mul_f32 v[4:5], v[76:77], v[84:85]
	v_pk_mul_f32 v[6:7], v[78:79], v[16:17]
	global_store_dwordx4 v[92:93], v[4:7], off offset:-2048
	s_nop 1
	v_pk_mul_f32 v[4:5], v[80:81], v[12:13]
	v_pk_mul_f32 v[6:7], v[82:83], v[10:11]
	global_store_dwordx4 v[92:93], v[4:7], off offset:-1024
	s_nop 1
	v_pk_mul_f32 v[4:5], v[52:53], v[90:91]
	v_pk_mul_f32 v[6:7], v[54:55], v[88:89]
	global_store_dwordx4 v[92:93], v[4:7], off
	s_nop 1
	v_pk_mul_f32 v[4:5], v[56:57], v[14:15]
	v_pk_mul_f32 v[6:7], v[58:59], v[86:87]
	global_store_dwordx4 v[92:93], v[4:7], off offset:1024
	s_nop 1
	v_pk_mul_f32 v[4:5], v[60:61], v[84:85]
	v_pk_mul_f32 v[6:7], v[62:63], v[16:17]
	global_store_dwordx4 v[92:93], v[4:7], off offset:2048
	s_nop 1
	v_pk_mul_f32 v[4:5], v[64:65], v[12:13]
	v_pk_mul_f32 v[6:7], v[66:67], v[10:11]
	global_store_dwordx4 v[92:93], v[4:7], off offset:3072
	s_nop 1
	v_pk_mul_f32 v[4:5], v[36:37], v[90:91]
	v_pk_mul_f32 v[6:7], v[38:39], v[88:89]
	global_store_dwordx4 v[254:255], v[4:7], off offset:-4096
	s_nop 1
	v_pk_mul_f32 v[4:5], v[40:41], v[14:15]
	v_pk_mul_f32 v[6:7], v[42:43], v[86:87]
	global_store_dwordx4 v[254:255], v[4:7], off offset:-3072
	s_nop 1
	v_pk_mul_f32 v[4:5], v[44:45], v[84:85]
	v_pk_mul_f32 v[6:7], v[46:47], v[16:17]
	global_store_dwordx4 v[254:255], v[4:7], off offset:-2048
	s_nop 1
	v_pk_mul_f32 v[4:5], v[48:49], v[12:13]
	v_pk_mul_f32 v[6:7], v[50:51], v[10:11]
	global_store_dwordx4 v[254:255], v[4:7], off offset:-1024
	s_nop 1
	v_pk_mul_f32 v[4:5], v[20:21], v[90:91]
	v_pk_mul_f32 v[6:7], v[22:23], v[88:89]
	global_store_dwordx4 v[254:255], v[4:7], off
	s_nop 1
	v_pk_mul_f32 v[4:5], v[24:25], v[14:15]
	v_pk_mul_f32 v[6:7], v[26:27], v[86:87]
	global_store_dwordx4 v[254:255], v[4:7], off offset:1024
	s_nop 1
	v_pk_mul_f32 v[4:5], v[28:29], v[84:85]
	v_pk_mul_f32 v[6:7], v[30:31], v[16:17]
	global_store_dwordx4 v[254:255], v[4:7], off offset:2048
	s_nop 1
	v_pk_mul_f32 v[4:5], v[32:33], v[12:13]
	v_pk_mul_f32 v[6:7], v[34:35], v[10:11]
	global_store_dwordx4 v[254:255], v[4:7], off offset:3072
	s_waitcnt vmcnt(0)
	s_barrier
	s_and_saveexec_b64 s[4:5], vcc
	s_cbranch_execz .LBB0_536
	v_lshlrev_b32_e32 v2, 4, v94
	buffer_wbl2 sc1
	s_waitcnt vmcnt(0)
	s_waitcnt vmcnt(0)
	v_lshlrev_b64 v[4:5], 2, v[2:3]
	v_lshl_add_u64 v[4:5], s[14:15], 0, v[4:5]
	global_store_dword v[4:5], v229, off sc1

; #define LAS __attribute__((address_space(3)))
; __device__ __forceinline__ unsigned f2bf(float f) { unsigned u = __builtin_bit_cast(unsigned, f); return (u + 0x7fffu + ((u >> 16) & 1u)) >> 16; }
; __device__ __forceinline__ int crow(int r, int hi) { return (r & 3) + 8 * (r >> 2) + 4 * hi; }
; template <bool NOMAX>
; __device__ __forceinline__ void diff_unit(const AttnCtx& C, int u, LAS unsigned char* lds) {
;     ...
;         const f32x4* st = (const f32x4*)(C.stash + (slot * 512 + tidf) * 64);
;         LAS bf16* stg = (LAS bf16*)(lds + TD_OST) + wid * (32 * 128);
; #pragma unroll
;         for (int d = 0; d < 4; ++d)
; #pragma unroll
;             for (int gq = 0; gq < 4; ++gq) { const f32x4 s1 = st[d * 4 + gq];
; #pragma unroll
;                 for (int e = 0; e < 4; ++e) { const int r = 4 * gq + e; stg[crow(r, hi) * 128 + 32 * d + r32] = (bf16)f2bf(s1[e] - C.lam * (o[d][r] * rli[r])); } }
.LBB0_640:
	s_or_b64 exec, exec, s[4:5]
	v_ashrrev_i32_e32 v9, 31, v8
	v_lshlrev_b64 v[4:5], 17, v[2:3]
	v_lshl_add_u64 v[4:5], s[12:13], 0, v[4:5]
	v_and_b32_e32 v6, 63, v8
	v_lshrrev_b32_e32 v7, 6, v8
	v_lshlrev_b32_e32 v6, 4, v6
	v_lshl_add_u32 v6, v7, 14, v6
	v_add_u32_e32 v6, 0x1000, v6
	v_mov_b32_e32 v7, 0
	s_mov_b64 s[98:99], 0x2000
	v_lshl_add_u64 v[30:31], v[4:5], 0, v[6:7]
	v_lshl_add_u64 v[254:255], v[30:31], 0, s[98:99]
	s_barrier
	global_load_dwordx4 v[98:101], v[30:31], off offset:-4096
	global_load_dwordx4 v[102:105], v[30:31], off offset:-3072
	global_load_dwordx4 v[106:109], v[30:31], off offset:-2048
	global_load_dwordx4 v[110:113], v[30:31], off offset:-1024
	global_load_dwordx4 v[4:7], v[30:31], off offset:1024
	global_load_dwordx4 v[114:117], v[30:31], off
	global_load_dwordx4 v[118:121], v[30:31], off offset:3072
	global_load_dwordx4 v[122:125], v[30:31], off offset:2048
	v_mul_f32_e32 v32, v82, v28
	s_lshl_b32 s0, s0, 1
	v_mul_f32_e32 v33, v83, v29
	v_mul_f32_e32 v126, v84, v26
	v_mul_f32_e32 v127, v85, v27
	v_mul_f32_e32 v128, v86, v14
	v_mul_f32_e32 v129, v87, v15
	v_mul_f32_e32 v130, v88, v24
	v_mul_f32_e32 v131, v89, v25
	v_mul_f32_e32 v132, v90, v22
	v_mul_f32_e32 v133, v91, v23
	v_mul_f32_e32 v134, v92, v20
	v_mul_f32_e32 v135, v93, v21
	v_mul_f32_e32 v136, v94, v12
	v_lshlrev_b32_e32 v9, 1, v236
	v_mul_f32_e32 v137, v95, v13
	s_add_i32 s0, s0, 0
	v_add3_u32 v9, s0, v9, v219
	v_readlane_b32 s6, v253, 60
	v_readlane_b32 s7, v253, 61
	v_mov_b32_e32 v219, v3
	v_readlane_b32 s60, v253, 32
	v_readlane_b32 s72, v253, 44
	v_readlane_b32 s73, v253, 45
	v_readlane_b32 s4, v253, 28
	v_readlane_b32 s5, v253, 29
	v_readlane_b32 s61, v253, 33
	v_readlane_b32 s62, v253, 34
	v_readlane_b32 s63, v253, 35
	v_readlane_b32 s64, v253, 36
	v_readlane_b32 s65, v253, 37
	v_readlane_b32 s66, v253, 38
	v_readlane_b32 s67, v253, 39
	v_readlane_b32 s68, v253, 40
	v_readlane_b32 s69, v253, 41
	v_readlane_b32 s70, v253, 42
	v_readlane_b32 s71, v253, 43
	v_readlane_b32 s74, v253, 46
	v_readlane_b32 s75, v253, 47
	s_waitcnt vmcnt(7)
	v_fma_f32 v32, -v216, v32, v98
	v_fma_f32 v33, -v216, v33, v99
	v_fma_f32 v98, -v216, v126, v100
	v_fma_f32 v99, -v216, v127, v101
	s_waitcnt vmcnt(6)
	v_fma_f32 v100, -v216, v128, v102
	v_fma_f32 v101, -v216, v129, v103
	v_fma_f32 v102, -v216, v130, v104
	v_fma_f32 v103, -v216, v131, v105
	s_waitcnt vmcnt(5)
	v_fma_f32 v104, -v216, v132, v106
	v_fma_f32 v105, -v216, v133, v107
	v_fma_f32 v106, -v216, v134, v108
	v_fma_f32 v107, -v216, v135, v109
	s_waitcnt vmcnt(4)
	v_fma_f32 v108, -v216, v136, v110
	v_bfe_u32 v110, v32, 16, 1
	v_fma_f32 v109, -v216, v137, v111
	v_bfe_u32 v111, v33, 16, 1
	v_bfe_u32 v126, v98, 16, 1
	v_bfe_u32 v127, v99, 16, 1
	v_bfe_u32 v128, v100, 16, 1
	v_bfe_u32 v129, v101, 16, 1
	v_bfe_u32 v130, v102, 16, 1
	v_bfe_u32 v131, v103, 16, 1
	v_bfe_u32 v132, v104, 16, 1
	v_bfe_u32 v133, v105, 16, 1
	v_bfe_u32 v134, v106, 16, 1
	v_bfe_u32 v135, v107, 16, 1
	v_bfe_u32 v136, v108, 16, 1
	v_add3_u32 v32, v32, v110, s55
	v_add3_u32 v33, v33, v111, s55
	v_add3_u32 v98, v98, v126, s55
	v_add3_u32 v99, v99, v127, s55
	v_add3_u32 v100, v100, v128, s55
	v_add3_u32 v101, v101, v129, s55
	v_add3_u32 v102, v102, v130, s55
	v_add3_u32 v103, v103, v131, s55
	v_add3_u32 v104, v104, v132, s55
	v_add3_u32 v105, v105, v133, s55
	v_add3_u32 v106, v106, v134, s55
	v_add3_u32 v107, v107, v135, s55
	v_add3_u32 v108, v108, v136, s55
	ds_write_b16_d16_hi v9, v32
	ds_write_b16_d16_hi v9, v33 offset:256
	ds_write_b16_d16_hi v9, v98 offset:512
	ds_write_b16_d16_hi v9, v99 offset:768
	ds_write_b16_d16_hi v9, v100 offset:2048
	ds_write_b16_d16_hi v9, v101 offset:2304
	ds_write_b16_d16_hi v9, v102 offset:2560
	ds_write_b16_d16_hi v9, v103 offset:2816
	ds_write_b16_d16_hi v9, v104 offset:4096
	ds_write_b16_d16_hi v9, v105 offset:4352
	ds_write_b16_d16_hi v9, v106 offset:4608
	ds_write_b16_d16_hi v9, v107 offset:4864
	ds_write_b16_d16_hi v9, v108 offset:6144
	v_bfe_u32 v32, v109, 16, 1
	v_add3_u32 v32, v109, v32, s55
	ds_write_b16_d16_hi v9, v32 offset:6400
	v_mul_f32_e32 v32, v96, v10
	v_fma_f32 v32, -v216, v32, v112
	v_bfe_u32 v33, v32, 16, 1
	v_add3_u32 v32, v32, v33, s55
	ds_write_b16_d16_hi v9, v32 offset:6656
	v_mul_f32_e32 v32, v97, v11
	v_fma_f32 v32, -v216, v32, v113
	v_bfe_u32 v33, v32, 16, 1
	v_add3_u32 v32, v32, v33, s55
	ds_write_b16_d16_hi v9, v32 offset:6912
	v_mul_f32_e32 v32, v66, v28
	s_waitcnt vmcnt(2)
	v_fma_f32 v32, -v216, v32, v114
	v_bfe_u32 v33, v32, 16, 1
	v_add3_u32 v32, v32, v33, s55
	global_load_dwordx4 v[98:101], v[254:255], off offset:-3072
	global_load_dwordx4 v[102:105], v[254:255], off offset:-4096
	ds_write_b16_d16_hi v9, v32 offset:64
	v_mul_f32_e32 v32, v67, v29
	v_fma_f32 v32, -v216, v32, v115
	v_bfe_u32 v33, v32, 16, 1
	v_add3_u32 v32, v32, v33, s55
	ds_write_b16_d16_hi v9, v32 offset:320
	v_mul_f32_e32 v32, v68, v26
	v_fma_f32 v32, -v216, v32, v116
	v_bfe_u32 v33, v32, 16, 1
	v_add3_u32 v32, v32, v33, s55
	ds_write_b16_d16_hi v9, v32 offset:576
	v_mul_f32_e32 v32, v69, v27
	v_fma_f32 v32, -v216, v32, v117
	v_bfe_u32 v33, v32, 16, 1
	v_add3_u32 v32, v32, v33, s55
	ds_write_b16_d16_hi v9, v32 offset:832
	v_mul_f32_e32 v32, v70, v14
	v_fma_f32 v4, -v216, v32, v4
	v_bfe_u32 v32, v4, 16, 1
	v_add3_u32 v4, v4, v32, s55
	ds_write_b16_d16_hi v9, v4 offset:2112
	v_mul_f32_e32 v4, v71, v15
	v_fma_f32 v4, -v216, v4, v5
	v_bfe_u32 v5, v4, 16, 1
	v_add3_u32 v4, v4, v5, s55
	ds_write_b16_d16_hi v9, v4 offset:2368
	v_mul_f32_e32 v4, v72, v24
	v_fma_f32 v4, -v216, v4, v6
	v_bfe_u32 v5, v4, 16, 1
	v_add3_u32 v4, v4, v5, s55
	ds_write_b16_d16_hi v9, v4 offset:2624
	v_mul_f32_e32 v4, v73, v25
	v_fma_f32 v4, -v216, v4, v7
	v_bfe_u32 v5, v4, 16, 1
	v_add3_u32 v4, v4, v5, s55
	ds_write_b16_d16_hi v9, v4 offset:2880
	v_mul_f32_e32 v4, v74, v22
	s_waitcnt vmcnt(2)
; #define LAS __attribute__((address_space(3)))
; __device__ __forceinline__ unsigned f2bf(float f) { unsigned u = __builtin_bit_cast(unsigned, f); return (u + 0x7fffu + ((u >> 16) & 1u)) >> 16; }
; __device__ __forceinline__ int crow(int r, int hi) { return (r & 3) + 8 * (r >> 2) + 4 * hi; }
; template <bool NOMAX>
; __device__ __forceinline__ void diff_unit(const AttnCtx& C, int u, LAS unsigned char* lds) {
;     ...
;         const f32x4* st = (const f32x4*)(C.stash + (slot * 512 + tidf) * 64);
;         LAS bf16* stg = (LAS bf16*)(lds + TD_OST) + wid * (32 * 128);
; #pragma unroll
;         for (int d = 0; d < 4; ++d)
; #pragma unroll
;             for (int gq = 0; gq < 4; ++gq) { const f32x4 s1 = st[d * 4 + gq];
; #pragma unroll
;                 for (int e = 0; e < 4; ++e) { const int r = 4 * gq + e; stg[crow(r, hi) * 128 + 32 * d + r32] = (bf16)f2bf(s1[e] - C.lam * (o[d][r] * rli[r])); } }
	v_fma_f32 v4, -v216, v4, v122
	v_bfe_u32 v5, v4, 16, 1
	v_add3_u32 v32, v4, v5, s55
	global_load_dwordx4 v[4:7], v[254:255], off offset:-1024
	global_load_dwordx4 v[106:109], v[254:255], off offset:-2048
	ds_write_b16_d16_hi v9, v32 offset:4160
	v_mul_f32_e32 v32, v75, v23
	v_fma_f32 v32, -v216, v32, v123
	v_bfe_u32 v33, v32, 16, 1
	v_add3_u32 v32, v32, v33, s55
	ds_write_b16_d16_hi v9, v32 offset:4416
	v_mul_f32_e32 v32, v76, v20
	v_fma_f32 v32, -v216, v32, v124
	v_bfe_u32 v33, v32, 16, 1
	v_add3_u32 v32, v32, v33, s55
	ds_write_b16_d16_hi v9, v32 offset:4672
	v_mul_f32_e32 v32, v77, v21
	v_fma_f32 v32, -v216, v32, v125
	v_bfe_u32 v33, v32, 16, 1
	v_add3_u32 v32, v32, v33, s55
	ds_write_b16_d16_hi v9, v32 offset:4928
	v_mul_f32_e32 v32, v78, v12
	v_fma_f32 v32, -v216, v32, v118
	v_bfe_u32 v33, v32, 16, 1
	v_add3_u32 v32, v32, v33, s55
	ds_write_b16_d16_hi v9, v32 offset:6208
	v_mul_f32_e32 v32, v79, v13
	v_fma_f32 v32, -v216, v32, v119
	v_bfe_u32 v33, v32, 16, 1
	v_add3_u32 v32, v32, v33, s55
	ds_write_b16_d16_hi v9, v32 offset:6464
	v_mul_f32_e32 v32, v80, v10
	v_fma_f32 v32, -v216, v32, v120
	v_bfe_u32 v33, v32, 16, 1
	v_add3_u32 v32, v32, v33, s55
	ds_write_b16_d16_hi v9, v32 offset:6720
	v_mul_f32_e32 v32, v81, v11
	v_fma_f32 v32, -v216, v32, v121
	v_bfe_u32 v33, v32, 16, 1
	v_add3_u32 v32, v32, v33, s55
	ds_write_b16_d16_hi v9, v32 offset:6976
	v_mul_f32_e32 v32, v50, v28
	global_load_dwordx4 v[110:113], v[254:255], off offset:1024
	global_load_dwordx4 v[114:117], v[254:255], off
	s_waitcnt vmcnt(4)
	v_fma_f32 v32, -v216, v32, v102
	v_bfe_u32 v33, v32, 16, 1
	v_add3_u32 v32, v32, v33, s55
	ds_write_b16_d16_hi v9, v32 offset:128
	v_mul_f32_e32 v32, v51, v29
	v_fma_f32 v32, -v216, v32, v103
	v_bfe_u32 v33, v32, 16, 1
	v_add3_u32 v32, v32, v33, s55
	ds_write_b16_d16_hi v9, v32 offset:384
	v_mul_f32_e32 v32, v52, v26
	v_fma_f32 v32, -v216, v32, v104
	v_bfe_u32 v33, v32, 16, 1
	v_add3_u32 v32, v32, v33, s55
	ds_write_b16_d16_hi v9, v32 offset:640
	v_mul_f32_e32 v32, v53, v27
	v_fma_f32 v32, -v216, v32, v105
	v_bfe_u32 v33, v32, 16, 1
	v_add3_u32 v32, v32, v33, s55
	ds_write_b16_d16_hi v9, v32 offset:896
	v_mul_f32_e32 v32, v54, v14
	v_fma_f32 v32, -v216, v32, v98
	v_bfe_u32 v33, v32, 16, 1
	v_add3_u32 v32, v32, v33, s55
	ds_write_b16_d16_hi v9, v32 offset:2176
	v_mul_f32_e32 v32, v55, v15
	v_fma_f32 v32, -v216, v32, v99
	v_bfe_u32 v33, v32, 16, 1
	v_add3_u32 v32, v32, v33, s55
	ds_write_b16_d16_hi v9, v32 offset:2432
	v_mul_f32_e32 v32, v56, v24
	v_fma_f32 v32, -v216, v32, v100
	v_bfe_u32 v33, v32, 16, 1
	v_add3_u32 v32, v32, v33, s55
	ds_write_b16_d16_hi v9, v32 offset:2688
	v_mul_f32_e32 v32, v57, v25
	v_fma_f32 v32, -v216, v32, v101
	v_bfe_u32 v33, v32, 16, 1
	v_add3_u32 v32, v32, v33, s55
	ds_write_b16_d16_hi v9, v32 offset:2944
	v_mul_f32_e32 v32, v58, v22
	s_waitcnt vmcnt(2)
	v_fma_f32 v102, -v216, v32, v106
	global_load_dwordx4 v[98:101], v[254:255], off offset:3072
	s_nop 0
	global_load_dwordx4 v[30:33], v[254:255], off offset:2048
	v_bfe_u32 v103, v102, 16, 1
	v_add3_u32 v102, v102, v103, s55
	ds_write_b16_d16_hi v9, v102 offset:4224
	v_mul_f32_e32 v102, v59, v23
	v_fma_f32 v102, -v216, v102, v107
	v_bfe_u32 v103, v102, 16, 1
	v_add3_u32 v102, v102, v103, s55
	ds_write_b16_d16_hi v9, v102 offset:4480
	v_mul_f32_e32 v102, v60, v20
	v_fma_f32 v102, -v216, v102, v108
	v_bfe_u32 v103, v102, 16, 1
	v_add3_u32 v102, v102, v103, s55
	ds_write_b16_d16_hi v9, v102 offset:4736
	v_mul_f32_e32 v102, v61, v21
	v_fma_f32 v102, -v216, v102, v109
	v_bfe_u32 v103, v102, 16, 1
	v_add3_u32 v102, v102, v103, s55
	ds_write_b16_d16_hi v9, v102 offset:4992
	v_mul_f32_e32 v102, v62, v12
	v_fma_f32 v4, -v216, v102, v4
	v_bfe_u32 v102, v4, 16, 1
	v_add3_u32 v4, v4, v102, s55
	ds_write_b16_d16_hi v9, v4 offset:6272
	v_mul_f32_e32 v4, v63, v13
	v_fma_f32 v4, -v216, v4, v5
	v_bfe_u32 v5, v4, 16, 1
	v_add3_u32 v4, v4, v5, s55
	ds_write_b16_d16_hi v9, v4 offset:6528
	v_mul_f32_e32 v4, v64, v10
	v_fma_f32 v4, -v216, v4, v6
	v_bfe_u32 v5, v4, 16, 1
	v_add3_u32 v4, v4, v5, s55
	ds_write_b16_d16_hi v9, v4 offset:6784
	v_mul_f32_e32 v4, v65, v11
	v_fma_f32 v4, -v216, v4, v7
	v_bfe_u32 v5, v4, 16, 1
	v_add3_u32 v4, v4, v5, s55
	ds_write_b16_d16_hi v9, v4 offset:7040
	v_mul_f32_e32 v4, v34, v28
	s_waitcnt vmcnt(2)
	v_fma_f32 v4, -v216, v4, v114
	v_bfe_u32 v5, v4, 16, 1
	v_add3_u32 v4, v4, v5, s55
	ds_write_b16_d16_hi v9, v4 offset:192
	v_mul_f32_e32 v4, v35, v29
	v_fma_f32 v4, -v216, v4, v115
	v_bfe_u32 v5, v4, 16, 1
	v_add3_u32 v4, v4, v5, s55
	ds_write_b16_d16_hi v9, v4 offset:448
	v_mul_f32_e32 v4, v36, v26
	v_fma_f32 v4, -v216, v4, v116
	v_bfe_u32 v5, v4, 16, 1
	v_add3_u32 v4, v4, v5, s55
	ds_write_b16_d16_hi v9, v4 offset:704
	v_mul_f32_e32 v4, v37, v27
	v_fma_f32 v4, -v216, v4, v117
	v_bfe_u32 v5, v4, 16, 1
	v_add3_u32 v4, v4, v5, s55
	ds_write_b16_d16_hi v9, v4 offset:960
	v_mul_f32_e32 v4, v38, v14
	v_fma_f32 v4, -v216, v4, v110
	v_bfe_u32 v5, v4, 16, 1
	v_add3_u32 v4, v4, v5, s55
	ds_write_b16_d16_hi v9, v4 offset:2240
	v_mul_f32_e32 v4, v39, v15
	v_fma_f32 v4, -v216, v4, v111
	v_bfe_u32 v5, v4, 16, 1
	v_add3_u32 v4, v4, v5, s55
	ds_write_b16_d16_hi v9, v4 offset:2496
	v_mul_f32_e32 v4, v40, v24
	v_fma_f32 v4, -v216, v4, v112
	v_bfe_u32 v5, v4, 16, 1
	v_add3_u32 v4, v4, v5, s55
	ds_write_b16_d16_hi v9, v4 offset:2752
	v_mul_f32_e32 v4, v41, v25
	v_fma_f32 v4, -v216, v4, v113
	v_bfe_u32 v5, v4, 16, 1
	v_add3_u32 v4, v4, v5, s55
	ds_write_b16_d16_hi v9, v4 offset:3008
	v_mul_f32_e32 v4, v42, v22
	s_waitcnt vmcnt(0)
; template <bool NOMAX>
; __device__ __forceinline__ void diff_unit(const AttnCtx& C, int u, LAS unsigned char* lds) {
;     ...
;                 for (int e = 0; e < 4; ++e) { const int r = 4 * gq + e; stg[crow(r, hi) * 128 + 32 * d + r32] = (bf16)f2bf(s1[e] - C.lam * (o[d][r] * rli[r])); } }
;         LDS_WAIT(); asm volatile("" ::: "memory");
;         const int cl = lanef & 15;
;         const size_t rowb = (size_t)(q0 + wid * 32);
; #pragma unroll
;         for (int ps = 0; ps < 8; ++ps) {
;             const int rl = ps * 4 + (lanef >> 4); const size_t row = rowb + rl;
;             const v4u sv = *(const LAS v4u*)(stg + rl * 128 + cl * 8);
;             float xv[8];
;             xv[0] = __builtin_bit_cast(float, sv.x << 16); xv[1] = __builtin_bit_cast(float, sv.x & 0xffff0000u); xv[2] = __builtin_bit_cast(float, sv.y << 16); xv[3] = __builtin_bit_cast(float, sv.y & 0xffff0000u);
;             xv[4] = __builtin_bit_cast(float, sv.z << 16); xv[5] = __builtin_bit_cast(float, sv.z & 0xffff0000u); xv[6] = __builtin_bit_cast(float, sv.w << 16); xv[7] = __builtin_bit_cast(float, sv.w & 0xffff0000u);
;             const v4u gv = *(const v4u*)(C.GD + row * 512 + h * 128 + cl * 8);
;             float gg[8];
;             gg[0] = __builtin_bit_cast(float, gv.x << 16); gg[1] = __builtin_bit_cast(float, gv.x & 0xffff0000u); gg[2] = __builtin_bit_cast(float, gv.y << 16); gg[3] = __builtin_bit_cast(float, gv.y & 0xffff0000u);
;             gg[4] = __builtin_bit_cast(float, gv.z << 16); gg[5] = __builtin_bit_cast(float, gv.z & 0xffff0000u); gg[6] = __builtin_bit_cast(float, gv.w << 16); gg[7] = __builtin_bit_cast(float, gv.w & 0xffff0000u);
;             float sq = 0.f;
; #pragma unroll
;             for (int e = 0; e < 8; ++e) sq += xv[e] * xv[e];
;     ...
;             SQDPP(0xB1); SQDPP(0x4E); SQDPP(0x141); SQDPP(0x140);
;     ...
;             const float rs = (1.0f / sqrtf(sq * (1.0f / 128.0f) + EPSN)) * 0.8f;
;             const f32x4 s0 = *(const f32x4*)(C.subln + cl * 8), s1 = *(const f32x4*)(C.subln + cl * 8 + 4);
; #pragma unroll
;             for (int e = 0; e < 4; ++e) { xv[e] *= rs * s0[e]; xv[4 + e] *= rs * s1[e]; }
;             v4u ov; ov.x = pk2(xv[0] * gg[0], xv[1] * gg[1]); ov.y = pk2(xv[2] * gg[2], xv[3] * gg[3]); ov.z = pk2(xv[4] * gg[4], xv[5] * gg[5]); ov.w = pk2(xv[6] * gg[6], xv[7] * gg[7]);
;             *(v4u*)(C.MIX + row * 1024 + 512 + h * 128 + cl * 8) = ov;
	v_fma_f32 v4, -v216, v4, v30
	v_bfe_u32 v5, v4, 16, 1
	v_add3_u32 v4, v4, v5, s55
	ds_write_b16_d16_hi v9, v4 offset:4288
	v_mul_f32_e32 v4, v43, v23
	v_fma_f32 v4, -v216, v4, v31
	v_bfe_u32 v5, v4, 16, 1
	v_add3_u32 v4, v4, v5, s55
	ds_write_b16_d16_hi v9, v4 offset:4544
	v_mul_f32_e32 v4, v44, v20
	v_fma_f32 v4, -v216, v4, v32
	v_bfe_u32 v5, v4, 16, 1
	v_add3_u32 v4, v4, v5, s55
	ds_write_b16_d16_hi v9, v4 offset:4800
	v_mul_f32_e32 v4, v45, v21
	v_fma_f32 v4, -v216, v4, v33
	v_bfe_u32 v5, v4, 16, 1
	v_add3_u32 v4, v4, v5, s55
	ds_write_b16_d16_hi v9, v4 offset:5056
	v_mul_f32_e32 v4, v46, v12
	v_fma_f32 v4, -v216, v4, v98
	v_bfe_u32 v5, v4, 16, 1
	v_add3_u32 v4, v4, v5, s55
	ds_write_b16_d16_hi v9, v4 offset:6336
	v_mul_f32_e32 v4, v47, v13
	v_fma_f32 v4, -v216, v4, v99
	v_bfe_u32 v5, v4, 16, 1
	v_add3_u32 v4, v4, v5, s55
	ds_write_b16_d16_hi v9, v4 offset:6592
	v_mul_f32_e32 v4, v48, v10
	v_fma_f32 v4, -v216, v4, v100
	v_bfe_u32 v5, v4, 16, 1
	v_add3_u32 v4, v4, v5, s55
	ds_write_b16_d16_hi v9, v4 offset:6848
	v_mul_f32_e32 v4, v49, v11
	v_fma_f32 v4, -v216, v4, v101
	v_bfe_u32 v5, v4, 16, 1
	v_bfe_u32 v6, v8, 4, 2
	v_add3_u32 v4, v4, v5, s55
	v_or_b32_e32 v110, v16, v6
	v_mov_b32_e32 v111, v17
	ds_write_b16_d16_hi v9, v4 offset:7104
	v_lshlrev_b32_e32 v4, 3, v8
	v_lshlrev_b64 v[30:31], 10, v[110:111]
	v_and_b32_e32 v7, 0x78, v4
	v_lshl_add_u64 v[30:31], s[6:7], 0, v[30:31]
	s_waitcnt lgkmcnt(0)
	v_lshlrev_b32_e32 v4, 1, v7
	v_lshl_add_u64 v[30:31], v[30:31], 0, v[218:219]
	v_mov_b32_e32 v5, v3
	v_lshl_add_u64 v[30:31], v[30:31], 0, v[4:5]
	global_load_dwordx4 v[30:33], v[30:31], off
	v_lshlrev_b32_e32 v7, 2, v7
	global_load_dwordx4 v[98:101], v7, s[72:73]
	global_load_dwordx4 v[102:105], v7, s[72:73] offset:16
	v_add_u32_e32 v9, s0, v4
	v_lshl_add_u32 v106, v6, 8, v9
	ds_read_b128 v[106:109], v106
	s_waitcnt lgkmcnt(0)
	v_lshlrev_b32_e32 v124, 16, v106
	v_and_b32_e32 v125, 0xffff0000, v106
	v_lshlrev_b32_e32 v120, 16, v107
	v_and_b32_e32 v121, 0xffff0000, v107
	v_pk_mul_f32 v[106:107], v[124:125], v[124:125]
	v_pk_mul_f32 v[122:123], v[120:121], v[120:121]
	v_lshlrev_b32_e32 v118, 16, v108
	v_and_b32_e32 v119, 0xffff0000, v108
	v_lshlrev_b32_e32 v112, 16, v109
	v_and_b32_e32 v113, 0xffff0000, v109
	v_pk_mul_f32 v[108:109], v[118:119], v[118:119]
	v_pk_mul_f32 v[116:117], v[112:113], v[112:113]
	s_waitcnt vmcnt(2)
	v_lshlrev_b32_e32 v114, 16, v33
	v_and_b32_e32 v115, 0xffff0000, v33
	v_add_f32_e32 v33, v106, v107
	v_add_f32_e32 v33, v122, v33
	v_add_f32_e32 v33, v123, v33
	v_add_f32_e32 v33, v108, v33
	v_add_f32_e32 v33, v109, v33
	v_add_f32_e32 v33, v116, v33
	v_add_f32_e32 v33, v117, v33
	v_and_b32_e32 v107, 0xffff0000, v32
	s_nop 0
	v_add_f32_dpp v33, v33, v33 quad_perm:[1,0,3,2] row_mask:0xf bank_mask:0xf bound_ctrl:1
	s_nop 1
	v_add_f32_dpp v33, v33, v33 quad_perm:[2,3,0,1] row_mask:0xf bank_mask:0xf bound_ctrl:1
	s_nop 1
	v_add_f32_dpp v33, v33, v33 row_half_mirror row_mask:0xf bank_mask:0xf bound_ctrl:1
	s_nop 1
	v_add_f32_dpp v33, v33, v33 row_mirror row_mask:0xf bank_mask:0xf bound_ctrl:1
	v_fmamk_f32 v33, v33, 0x3c000000, v217
	v_mul_f32_e32 v106, 0x4f800000, v33
	v_cmp_gt_f32_e32 vcc, s56, v33
	s_nop 1
	v_cndmask_b32_e32 v33, v33, v106, vcc
	v_sqrt_f32_e32 v108, v33
	v_lshlrev_b32_e32 v106, 16, v32
	v_lshlrev_b32_e32 v32, 16, v31
	v_add_u32_e32 v109, -1, v108
	v_fma_f32 v116, -v109, v108, v33
	v_cmp_ge_f32_e64 s[2:3], 0, v116
	v_add_u32_e32 v116, 1, v108
	s_nop 0
	v_cndmask_b32_e64 v109, v108, v109, s[2:3]
	v_fma_f32 v108, -v116, v108, v33
	v_cmp_lt_f32_e64 s[2:3], 0, v108
	s_nop 1
	v_cndmask_b32_e64 v108, v109, v116, s[2:3]
	v_mul_f32_e32 v109, 0x37800000, v108
	v_cndmask_b32_e32 v108, v108, v109, vcc
	v_cmp_class_f32_e32 vcc, v33, v228
	v_and_b32_e32 v109, 0xffff0000, v30
	s_nop 0
	v_cndmask_b32_e32 v116, v108, v33, vcc
	v_div_scale_f32 v117, s[0:1], v116, v116, 1.0
	v_rcp_f32_e32 v122, v117
	v_lshlrev_b32_e32 v108, 16, v30
	v_and_b32_e32 v33, 0xffff0000, v31
	v_fma_f32 v30, -v117, v122, 1.0
	v_fmac_f32_e32 v122, v30, v122
	v_div_scale_f32 v30, vcc, 1.0, v116, 1.0
	v_mul_f32_e32 v31, v30, v122
	v_fma_f32 v123, -v117, v31, v30
	v_fmac_f32_e32 v31, v123, v122
	v_fma_f32 v30, -v117, v31, v30
	v_div_fmas_f32 v30, v30, v122, v31
	v_div_fixup_f32 v30, v30, v116, 1.0
	v_mul_f32_e32 v30, 0x3f4ccccd, v30
	s_waitcnt vmcnt(1)
	v_pk_mul_f32 v[98:99], v[98:99], v[30:31] op_sel_hi:[1,0]
	v_pk_mul_f32 v[100:101], v[100:101], v[30:31] op_sel_hi:[1,0]
	v_pk_mul_f32 v[98:99], v[98:99], v[124:125]
	s_waitcnt vmcnt(0)
	v_pk_mul_f32 v[102:103], v[102:103], v[30:31] op_sel_hi:[1,0]
	v_pk_mul_f32 v[100:101], v[100:101], v[120:121]
	v_pk_mul_f32 v[30:31], v[104:105], v[30:31] op_sel_hi:[1,0]
	v_pk_mul_f32 v[102:103], v[102:103], v[118:119]
	v_pk_mul_f32 v[104:105], v[30:31], v[112:113]
	v_pk_mul_f32 v[30:31], v[98:99], v[108:109]
	v_pk_mul_f32 v[32:33], v[100:101], v[32:33]
	v_cvt_pk_bf16_f32 v30, v30, v31
	v_cvt_pk_bf16_f32 v31, v32, v33
	v_pk_mul_f32 v[32:33], v[102:103], v[106:107]
	v_pk_mul_f32 v[98:99], v[104:105], v[114:115]
	v_cvt_pk_bf16_f32 v32, v32, v33
	v_cvt_pk_bf16_f32 v33, v98, v99
	v_lshlrev_b64 v[98:99], 11, v[110:111]
	v_lshl_add_u64 v[98:99], s[4:5], 0, v[98:99]
	v_lshl_add_u64 v[98:99], v[98:99], 0, v[218:219]
	v_or_b32_e32 v106, 4, v6
	v_lshl_add_u64 v[98:99], v[98:99], 0, v[4:5]
	v_or_b32_e32 v110, v16, v106
	global_store_dwordx4 v[98:99], v[30:33], off offset:1024
	v_lshl_add_u32 v106, v106, 8, v9
	s_nop 0
	v_lshlrev_b64 v[30:31], 10, v[110:111]
	v_lshl_add_u64 v[30:31], s[6:7], 0, v[30:31]
	v_lshl_add_u64 v[30:31], v[30:31], 0, v[218:219]
	v_lshl_add_u64 v[30:31], v[30:31], 0, v[4:5]
	global_load_dwordx4 v[30:33], v[30:31], off
	s_nop 0
	global_load_dwordx4 v[98:101], v7, s[72:73]
	global_load_dwordx4 v[102:105], v7, s[72:73] offset:16
	ds_read_b128 v[106:109], v106
	s_waitcnt lgkmcnt(0)
; #define LAS __attribute__((address_space(3)))
; __device__ __forceinline__ unsigned pk2(float lo, float hi) { f32x2_t v = {lo, hi}; bf16x2_t b = __builtin_convertvector(v, bf16x2_t); return __builtin_bit_cast(unsigned, b); }
; template <bool NOMAX>
; __device__ __forceinline__ void diff_unit(const AttnCtx& C, int u, LAS unsigned char* lds) {
;     ...
;         for (int ps = 0; ps < 8; ++ps) {
;             const int rl = ps * 4 + (lanef >> 4); const size_t row = rowb + rl;
;             const v4u sv = *(const LAS v4u*)(stg + rl * 128 + cl * 8);
;             float xv[8];
;             xv[0] = __builtin_bit_cast(float, sv.x << 16); xv[1] = __builtin_bit_cast(float, sv.x & 0xffff0000u); xv[2] = __builtin_bit_cast(float, sv.y << 16); xv[3] = __builtin_bit_cast(float, sv.y & 0xffff0000u);
;             xv[4] = __builtin_bit_cast(float, sv.z << 16); xv[5] = __builtin_bit_cast(float, sv.z & 0xffff0000u); xv[6] = __builtin_bit_cast(float, sv.w << 16); xv[7] = __builtin_bit_cast(float, sv.w & 0xffff0000u);
;             const v4u gv = *(const v4u*)(C.GD + row * 512 + h * 128 + cl * 8);
;             float gg[8];
;             gg[0] = __builtin_bit_cast(float, gv.x << 16); gg[1] = __builtin_bit_cast(float, gv.x & 0xffff0000u); gg[2] = __builtin_bit_cast(float, gv.y << 16); gg[3] = __builtin_bit_cast(float, gv.y & 0xffff0000u);
;             gg[4] = __builtin_bit_cast(float, gv.z << 16); gg[5] = __builtin_bit_cast(float, gv.z & 0xffff0000u); gg[6] = __builtin_bit_cast(float, gv.w << 16); gg[7] = __builtin_bit_cast(float, gv.w & 0xffff0000u);
;             float sq = 0.f;
; #pragma unroll
;             for (int e = 0; e < 8; ++e) sq += xv[e] * xv[e];
;     ...
;             SQDPP(0xB1); SQDPP(0x4E); SQDPP(0x141); SQDPP(0x140);
;     ...
;             const float rs = (1.0f / sqrtf(sq * (1.0f / 128.0f) + EPSN)) * 0.8f;
;             const f32x4 s0 = *(const f32x4*)(C.subln + cl * 8), s1 = *(const f32x4*)(C.subln + cl * 8 + 4);
; #pragma unroll
;             for (int e = 0; e < 4; ++e) { xv[e] *= rs * s0[e]; xv[4 + e] *= rs * s1[e]; }
;             v4u ov; ov.x = pk2(xv[0] * gg[0], xv[1] * gg[1]); ov.y = pk2(xv[2] * gg[2], xv[3] * gg[3]); ov.z = pk2(xv[4] * gg[4], xv[5] * gg[5]); ov.w = pk2(xv[6] * gg[6], xv[7] * gg[7]);
;             *(v4u*)(C.MIX + row * 1024 + 512 + h * 128 + cl * 8) = ov;
	v_lshlrev_b32_e32 v124, 16, v106
	v_and_b32_e32 v125, 0xffff0000, v106
	v_lshlrev_b32_e32 v120, 16, v107
	v_and_b32_e32 v121, 0xffff0000, v107
	v_pk_mul_f32 v[106:107], v[124:125], v[124:125]
	v_pk_mul_f32 v[122:123], v[120:121], v[120:121]
	v_lshlrev_b32_e32 v118, 16, v108
	v_and_b32_e32 v119, 0xffff0000, v108
	v_lshlrev_b32_e32 v112, 16, v109
	v_and_b32_e32 v113, 0xffff0000, v109
	v_pk_mul_f32 v[108:109], v[118:119], v[118:119]
	v_pk_mul_f32 v[116:117], v[112:113], v[112:113]
	s_waitcnt vmcnt(2)
	v_lshlrev_b32_e32 v114, 16, v33
	v_and_b32_e32 v115, 0xffff0000, v33
	v_add_f32_e32 v33, v106, v107
	v_add_f32_e32 v33, v122, v33
	v_add_f32_e32 v33, v123, v33
	v_add_f32_e32 v33, v108, v33
	v_add_f32_e32 v33, v109, v33
	v_add_f32_e32 v33, v116, v33
	v_add_f32_e32 v33, v117, v33
	v_and_b32_e32 v107, 0xffff0000, v32
	s_nop 0
	v_add_f32_dpp v33, v33, v33 quad_perm:[1,0,3,2] row_mask:0xf bank_mask:0xf bound_ctrl:1
	s_nop 1
	v_add_f32_dpp v33, v33, v33 quad_perm:[2,3,0,1] row_mask:0xf bank_mask:0xf bound_ctrl:1
	s_nop 1
	v_add_f32_dpp v33, v33, v33 row_half_mirror row_mask:0xf bank_mask:0xf bound_ctrl:1
	s_nop 1
	v_add_f32_dpp v33, v33, v33 row_mirror row_mask:0xf bank_mask:0xf bound_ctrl:1
	v_fmamk_f32 v33, v33, 0x3c000000, v217
	v_mul_f32_e32 v106, 0x4f800000, v33
	v_cmp_gt_f32_e32 vcc, s56, v33
	s_nop 1
	v_cndmask_b32_e32 v33, v33, v106, vcc
	v_sqrt_f32_e32 v108, v33
	v_lshlrev_b32_e32 v106, 16, v32
	v_lshlrev_b32_e32 v32, 16, v31
	v_add_u32_e32 v109, -1, v108
	v_fma_f32 v116, -v109, v108, v33
	v_cmp_ge_f32_e64 s[2:3], 0, v116
	v_add_u32_e32 v116, 1, v108
	s_nop 0
	v_cndmask_b32_e64 v109, v108, v109, s[2:3]
	v_fma_f32 v108, -v116, v108, v33
	v_cmp_lt_f32_e64 s[2:3], 0, v108
	s_nop 1
	v_cndmask_b32_e64 v108, v109, v116, s[2:3]
	v_mul_f32_e32 v109, 0x37800000, v108
	v_cndmask_b32_e32 v108, v108, v109, vcc
	v_cmp_class_f32_e32 vcc, v33, v228
	v_and_b32_e32 v109, 0xffff0000, v30
	s_nop 0
	v_cndmask_b32_e32 v116, v108, v33, vcc
	v_div_scale_f32 v117, s[0:1], v116, v116, 1.0
	v_rcp_f32_e32 v122, v117
	v_lshlrev_b32_e32 v108, 16, v30
	v_and_b32_e32 v33, 0xffff0000, v31
	v_fma_f32 v30, -v117, v122, 1.0
	v_fmac_f32_e32 v122, v30, v122
	v_div_scale_f32 v30, vcc, 1.0, v116, 1.0
	v_mul_f32_e32 v31, v30, v122
	v_fma_f32 v123, -v117, v31, v30
	v_fmac_f32_e32 v31, v123, v122
	v_fma_f32 v30, -v117, v31, v30
	v_div_fmas_f32 v30, v30, v122, v31
	v_div_fixup_f32 v30, v30, v116, 1.0
	v_mul_f32_e32 v30, 0x3f4ccccd, v30
	s_waitcnt vmcnt(1)
	v_pk_mul_f32 v[98:99], v[98:99], v[30:31] op_sel_hi:[1,0]
	v_pk_mul_f32 v[100:101], v[100:101], v[30:31] op_sel_hi:[1,0]
	v_pk_mul_f32 v[98:99], v[98:99], v[124:125]
	s_waitcnt vmcnt(0)
	v_pk_mul_f32 v[102:103], v[102:103], v[30:31] op_sel_hi:[1,0]
	v_pk_mul_f32 v[100:101], v[100:101], v[120:121]
	v_pk_mul_f32 v[30:31], v[104:105], v[30:31] op_sel_hi:[1,0]
	v_pk_mul_f32 v[102:103], v[102:103], v[118:119]
	v_pk_mul_f32 v[104:105], v[30:31], v[112:113]
	v_pk_mul_f32 v[30:31], v[98:99], v[108:109]
	v_pk_mul_f32 v[32:33], v[100:101], v[32:33]
	v_cvt_pk_bf16_f32 v30, v30, v31
	v_cvt_pk_bf16_f32 v31, v32, v33
	v_pk_mul_f32 v[32:33], v[102:103], v[106:107]
	v_pk_mul_f32 v[98:99], v[104:105], v[114:115]
	v_cvt_pk_bf16_f32 v32, v32, v33
	v_cvt_pk_bf16_f32 v33, v98, v99
	v_lshlrev_b64 v[98:99], 11, v[110:111]
	v_lshl_add_u64 v[98:99], s[4:5], 0, v[98:99]
	v_lshl_add_u64 v[98:99], v[98:99], 0, v[218:219]
	v_or_b32_e32 v106, 8, v6
	v_lshl_add_u64 v[98:99], v[98:99], 0, v[4:5]
	v_or_b32_e32 v110, v16, v106
	global_store_dwordx4 v[98:99], v[30:33], off offset:1024
	v_lshl_add_u32 v106, v106, 8, v9
	s_nop 0
	v_lshlrev_b64 v[30:31], 10, v[110:111]
	v_lshl_add_u64 v[30:31], s[6:7], 0, v[30:31]
	v_lshl_add_u64 v[30:31], v[30:31], 0, v[218:219]
	v_lshl_add_u64 v[30:31], v[30:31], 0, v[4:5]
	global_load_dwordx4 v[30:33], v[30:31], off
	s_nop 0
	global_load_dwordx4 v[98:101], v7, s[72:73]
	global_load_dwordx4 v[102:105], v7, s[72:73] offset:16
	ds_read_b128 v[106:109], v106
	s_waitcnt lgkmcnt(0)
	v_lshlrev_b32_e32 v124, 16, v106
	v_and_b32_e32 v125, 0xffff0000, v106
	v_lshlrev_b32_e32 v120, 16, v107
	v_and_b32_e32 v121, 0xffff0000, v107
	v_pk_mul_f32 v[106:107], v[124:125], v[124:125]
	v_pk_mul_f32 v[122:123], v[120:121], v[120:121]
	v_lshlrev_b32_e32 v118, 16, v108
	v_and_b32_e32 v119, 0xffff0000, v108
	v_lshlrev_b32_e32 v112, 16, v109
	v_and_b32_e32 v113, 0xffff0000, v109
	v_pk_mul_f32 v[108:109], v[118:119], v[118:119]
	v_pk_mul_f32 v[116:117], v[112:113], v[112:113]
	s_waitcnt vmcnt(2)
	v_lshlrev_b32_e32 v114, 16, v33
	v_and_b32_e32 v115, 0xffff0000, v33
	v_add_f32_e32 v33, v106, v107
	v_add_f32_e32 v33, v122, v33
	v_add_f32_e32 v33, v123, v33
	v_add_f32_e32 v33, v108, v33
	v_add_f32_e32 v33, v109, v33
	v_add_f32_e32 v33, v116, v33
	v_add_f32_e32 v33, v117, v33
	v_and_b32_e32 v107, 0xffff0000, v32
	s_nop 0
	v_add_f32_dpp v33, v33, v33 quad_perm:[1,0,3,2] row_mask:0xf bank_mask:0xf bound_ctrl:1
	s_nop 1
	v_add_f32_dpp v33, v33, v33 quad_perm:[2,3,0,1] row_mask:0xf bank_mask:0xf bound_ctrl:1
	s_nop 1
	v_add_f32_dpp v33, v33, v33 row_half_mirror row_mask:0xf bank_mask:0xf bound_ctrl:1
	s_nop 1
	v_add_f32_dpp v33, v33, v33 row_mirror row_mask:0xf bank_mask:0xf bound_ctrl:1
	v_fmamk_f32 v33, v33, 0x3c000000, v217
	v_mul_f32_e32 v106, 0x4f800000, v33
	v_cmp_gt_f32_e32 vcc, s56, v33
	s_nop 1
	v_cndmask_b32_e32 v33, v33, v106, vcc
	v_sqrt_f32_e32 v108, v33
	v_lshlrev_b32_e32 v106, 16, v32
	v_lshlrev_b32_e32 v32, 16, v31
	v_add_u32_e32 v109, -1, v108
	v_fma_f32 v116, -v109, v108, v33
	v_cmp_ge_f32_e64 s[2:3], 0, v116
	v_add_u32_e32 v116, 1, v108
	s_nop 0
	v_cndmask_b32_e64 v109, v108, v109, s[2:3]
	v_fma_f32 v108, -v116, v108, v33
	v_cmp_lt_f32_e64 s[2:3], 0, v108
	s_nop 1
	v_cndmask_b32_e64 v108, v109, v116, s[2:3]
	v_mul_f32_e32 v109, 0x37800000, v108
	v_cndmask_b32_e32 v108, v108, v109, vcc
	v_cmp_class_f32_e32 vcc, v33, v228
	v_and_b32_e32 v109, 0xffff0000, v30
	s_nop 0
	v_cndmask_b32_e32 v116, v108, v33, vcc
	v_div_scale_f32 v117, s[0:1], v116, v116, 1.0
	v_rcp_f32_e32 v122, v117
	v_lshlrev_b32_e32 v108, 16, v30
	v_and_b32_e32 v33, 0xffff0000, v31
	v_fma_f32 v30, -v117, v122, 1.0
	v_fmac_f32_e32 v122, v30, v122
	v_div_scale_f32 v30, vcc, 1.0, v116, 1.0
	v_mul_f32_e32 v31, v30, v122
	v_fma_f32 v123, -v117, v31, v30
	v_fmac_f32_e32 v31, v123, v122
	v_fma_f32 v30, -v117, v31, v30
	v_div_fmas_f32 v30, v30, v122, v31
	v_div_fixup_f32 v30, v30, v116, 1.0
	v_mul_f32_e32 v30, 0x3f4ccccd, v30
	s_waitcnt vmcnt(1)
; #define LAS __attribute__((address_space(3)))
; __device__ __forceinline__ unsigned pk2(float lo, float hi) { f32x2_t v = {lo, hi}; bf16x2_t b = __builtin_convertvector(v, bf16x2_t); return __builtin_bit_cast(unsigned, b); }
; template <bool NOMAX>
; __device__ __forceinline__ void diff_unit(const AttnCtx& C, int u, LAS unsigned char* lds) {
;     ...
;         for (int ps = 0; ps < 8; ++ps) {
;             const int rl = ps * 4 + (lanef >> 4); const size_t row = rowb + rl;
;             const v4u sv = *(const LAS v4u*)(stg + rl * 128 + cl * 8);
;             float xv[8];
;             xv[0] = __builtin_bit_cast(float, sv.x << 16); xv[1] = __builtin_bit_cast(float, sv.x & 0xffff0000u); xv[2] = __builtin_bit_cast(float, sv.y << 16); xv[3] = __builtin_bit_cast(float, sv.y & 0xffff0000u);
;             xv[4] = __builtin_bit_cast(float, sv.z << 16); xv[5] = __builtin_bit_cast(float, sv.z & 0xffff0000u); xv[6] = __builtin_bit_cast(float, sv.w << 16); xv[7] = __builtin_bit_cast(float, sv.w & 0xffff0000u);
;             const v4u gv = *(const v4u*)(C.GD + row * 512 + h * 128 + cl * 8);
;             float gg[8];
;             gg[0] = __builtin_bit_cast(float, gv.x << 16); gg[1] = __builtin_bit_cast(float, gv.x & 0xffff0000u); gg[2] = __builtin_bit_cast(float, gv.y << 16); gg[3] = __builtin_bit_cast(float, gv.y & 0xffff0000u);
;             gg[4] = __builtin_bit_cast(float, gv.z << 16); gg[5] = __builtin_bit_cast(float, gv.z & 0xffff0000u); gg[6] = __builtin_bit_cast(float, gv.w << 16); gg[7] = __builtin_bit_cast(float, gv.w & 0xffff0000u);
;             float sq = 0.f;
; #pragma unroll
;             for (int e = 0; e < 8; ++e) sq += xv[e] * xv[e];
;     ...
;             SQDPP(0xB1); SQDPP(0x4E); SQDPP(0x141); SQDPP(0x140);
;     ...
;             const float rs = (1.0f / sqrtf(sq * (1.0f / 128.0f) + EPSN)) * 0.8f;
;             const f32x4 s0 = *(const f32x4*)(C.subln + cl * 8), s1 = *(const f32x4*)(C.subln + cl * 8 + 4);
; #pragma unroll
;             for (int e = 0; e < 4; ++e) { xv[e] *= rs * s0[e]; xv[4 + e] *= rs * s1[e]; }
;             v4u ov; ov.x = pk2(xv[0] * gg[0], xv[1] * gg[1]); ov.y = pk2(xv[2] * gg[2], xv[3] * gg[3]); ov.z = pk2(xv[4] * gg[4], xv[5] * gg[5]); ov.w = pk2(xv[6] * gg[6], xv[7] * gg[7]);
;             *(v4u*)(C.MIX + row * 1024 + 512 + h * 128 + cl * 8) = ov;
	v_pk_mul_f32 v[98:99], v[98:99], v[30:31] op_sel_hi:[1,0]
	v_pk_mul_f32 v[100:101], v[100:101], v[30:31] op_sel_hi:[1,0]
	v_pk_mul_f32 v[98:99], v[98:99], v[124:125]
	s_waitcnt vmcnt(0)
	v_pk_mul_f32 v[102:103], v[102:103], v[30:31] op_sel_hi:[1,0]
	v_pk_mul_f32 v[100:101], v[100:101], v[120:121]
	v_pk_mul_f32 v[30:31], v[104:105], v[30:31] op_sel_hi:[1,0]
	v_pk_mul_f32 v[102:103], v[102:103], v[118:119]
	v_pk_mul_f32 v[104:105], v[30:31], v[112:113]
	v_pk_mul_f32 v[30:31], v[98:99], v[108:109]
	v_pk_mul_f32 v[32:33], v[100:101], v[32:33]
	v_cvt_pk_bf16_f32 v30, v30, v31
	v_cvt_pk_bf16_f32 v31, v32, v33
	v_pk_mul_f32 v[32:33], v[102:103], v[106:107]
	v_pk_mul_f32 v[98:99], v[104:105], v[114:115]
	v_cvt_pk_bf16_f32 v32, v32, v33
	v_cvt_pk_bf16_f32 v33, v98, v99
	v_lshlrev_b64 v[98:99], 11, v[110:111]
	v_lshl_add_u64 v[98:99], s[4:5], 0, v[98:99]
	v_lshl_add_u64 v[98:99], v[98:99], 0, v[218:219]
	v_or_b32_e32 v106, 12, v6
	v_lshl_add_u64 v[98:99], v[98:99], 0, v[4:5]
	v_or_b32_e32 v110, v16, v106
	global_store_dwordx4 v[98:99], v[30:33], off offset:1024
	v_lshl_add_u32 v106, v106, 8, v9
	s_nop 0
	v_lshlrev_b64 v[30:31], 10, v[110:111]
	v_lshl_add_u64 v[30:31], s[6:7], 0, v[30:31]
	v_lshl_add_u64 v[30:31], v[30:31], 0, v[218:219]
	v_lshl_add_u64 v[30:31], v[30:31], 0, v[4:5]
	global_load_dwordx4 v[30:33], v[30:31], off
	s_nop 0
	global_load_dwordx4 v[98:101], v7, s[72:73]
	global_load_dwordx4 v[102:105], v7, s[72:73] offset:16
	ds_read_b128 v[106:109], v106
	s_waitcnt lgkmcnt(0)
	v_lshlrev_b32_e32 v124, 16, v106
	v_and_b32_e32 v125, 0xffff0000, v106
	v_lshlrev_b32_e32 v120, 16, v107
	v_and_b32_e32 v121, 0xffff0000, v107
	v_pk_mul_f32 v[106:107], v[124:125], v[124:125]
	v_pk_mul_f32 v[122:123], v[120:121], v[120:121]
	v_lshlrev_b32_e32 v118, 16, v108
	v_and_b32_e32 v119, 0xffff0000, v108
	v_lshlrev_b32_e32 v112, 16, v109
	v_and_b32_e32 v113, 0xffff0000, v109
	v_pk_mul_f32 v[108:109], v[118:119], v[118:119]
	v_pk_mul_f32 v[116:117], v[112:113], v[112:113]
	s_waitcnt vmcnt(2)
	v_lshlrev_b32_e32 v114, 16, v33
	v_and_b32_e32 v115, 0xffff0000, v33
	v_add_f32_e32 v33, v106, v107
	v_add_f32_e32 v33, v122, v33
	v_add_f32_e32 v33, v123, v33
	v_add_f32_e32 v33, v108, v33
	v_add_f32_e32 v33, v109, v33
	v_add_f32_e32 v33, v116, v33
	v_add_f32_e32 v33, v117, v33
	v_and_b32_e32 v107, 0xffff0000, v32
	s_nop 0
	v_add_f32_dpp v33, v33, v33 quad_perm:[1,0,3,2] row_mask:0xf bank_mask:0xf bound_ctrl:1
	s_nop 1
	v_add_f32_dpp v33, v33, v33 quad_perm:[2,3,0,1] row_mask:0xf bank_mask:0xf bound_ctrl:1
	s_nop 1
	v_add_f32_dpp v33, v33, v33 row_half_mirror row_mask:0xf bank_mask:0xf bound_ctrl:1
	s_nop 1
	v_add_f32_dpp v33, v33, v33 row_mirror row_mask:0xf bank_mask:0xf bound_ctrl:1
	v_fmamk_f32 v33, v33, 0x3c000000, v217
	v_mul_f32_e32 v106, 0x4f800000, v33
	v_cmp_gt_f32_e32 vcc, s56, v33
	s_nop 1
	v_cndmask_b32_e32 v33, v33, v106, vcc
	v_sqrt_f32_e32 v108, v33
	v_lshlrev_b32_e32 v106, 16, v32
	v_lshlrev_b32_e32 v32, 16, v31
	v_add_u32_e32 v109, -1, v108
	v_fma_f32 v116, -v109, v108, v33
	v_cmp_ge_f32_e64 s[2:3], 0, v116
	v_add_u32_e32 v116, 1, v108
	s_nop 0
	v_cndmask_b32_e64 v109, v108, v109, s[2:3]
	v_fma_f32 v108, -v116, v108, v33
	v_cmp_lt_f32_e64 s[2:3], 0, v108
	s_nop 1
	v_cndmask_b32_e64 v108, v109, v116, s[2:3]
	v_mul_f32_e32 v109, 0x37800000, v108
	v_cndmask_b32_e32 v108, v108, v109, vcc
	v_cmp_class_f32_e32 vcc, v33, v228
	v_and_b32_e32 v109, 0xffff0000, v30
	s_nop 0
	v_cndmask_b32_e32 v116, v108, v33, vcc
	v_div_scale_f32 v117, s[0:1], v116, v116, 1.0
	v_rcp_f32_e32 v122, v117
	v_lshlrev_b32_e32 v108, 16, v30
	v_and_b32_e32 v33, 0xffff0000, v31
	v_fma_f32 v30, -v117, v122, 1.0
	v_fmac_f32_e32 v122, v30, v122
	v_div_scale_f32 v30, vcc, 1.0, v116, 1.0
	v_mul_f32_e32 v31, v30, v122
	v_fma_f32 v123, -v117, v31, v30
	v_fmac_f32_e32 v31, v123, v122
	v_fma_f32 v30, -v117, v31, v30
	v_div_fmas_f32 v30, v30, v122, v31
	v_div_fixup_f32 v30, v30, v116, 1.0
	v_mul_f32_e32 v30, 0x3f4ccccd, v30
	s_waitcnt vmcnt(1)
	v_pk_mul_f32 v[98:99], v[98:99], v[30:31] op_sel_hi:[1,0]
	v_pk_mul_f32 v[100:101], v[100:101], v[30:31] op_sel_hi:[1,0]
	v_pk_mul_f32 v[98:99], v[98:99], v[124:125]
	s_waitcnt vmcnt(0)
	v_pk_mul_f32 v[102:103], v[102:103], v[30:31] op_sel_hi:[1,0]
	v_pk_mul_f32 v[100:101], v[100:101], v[120:121]
	v_pk_mul_f32 v[30:31], v[104:105], v[30:31] op_sel_hi:[1,0]
	v_pk_mul_f32 v[102:103], v[102:103], v[118:119]
	v_pk_mul_f32 v[104:105], v[30:31], v[112:113]
	v_pk_mul_f32 v[30:31], v[98:99], v[108:109]
	v_pk_mul_f32 v[32:33], v[100:101], v[32:33]
	v_cvt_pk_bf16_f32 v30, v30, v31
	v_cvt_pk_bf16_f32 v31, v32, v33
	v_pk_mul_f32 v[32:33], v[102:103], v[106:107]
	v_pk_mul_f32 v[98:99], v[104:105], v[114:115]
	v_cvt_pk_bf16_f32 v32, v32, v33
	v_cvt_pk_bf16_f32 v33, v98, v99
	v_lshlrev_b64 v[98:99], 11, v[110:111]
	v_lshl_add_u64 v[98:99], s[4:5], 0, v[98:99]
	v_lshl_add_u64 v[98:99], v[98:99], 0, v[218:219]
	v_or_b32_e32 v106, 16, v6
	v_lshl_add_u64 v[98:99], v[98:99], 0, v[4:5]
	v_or_b32_e32 v110, v16, v106
	global_store_dwordx4 v[98:99], v[30:33], off offset:1024
	v_lshl_add_u32 v106, v106, 8, v9
	s_nop 0
	v_lshlrev_b64 v[30:31], 10, v[110:111]
	v_lshl_add_u64 v[30:31], s[6:7], 0, v[30:31]
	v_lshl_add_u64 v[30:31], v[30:31], 0, v[218:219]
	v_lshl_add_u64 v[30:31], v[30:31], 0, v[4:5]
	global_load_dwordx4 v[30:33], v[30:31], off
	s_nop 0
	global_load_dwordx4 v[98:101], v7, s[72:73]
	global_load_dwordx4 v[102:105], v7, s[72:73] offset:16
	ds_read_b128 v[106:109], v106
	s_waitcnt lgkmcnt(0)
; #define LAS __attribute__((address_space(3)))
; __device__ __forceinline__ unsigned pk2(float lo, float hi) { f32x2_t v = {lo, hi}; bf16x2_t b = __builtin_convertvector(v, bf16x2_t); return __builtin_bit_cast(unsigned, b); }
; template <bool NOMAX>
; __device__ __forceinline__ void diff_unit(const AttnCtx& C, int u, LAS unsigned char* lds) {
;     ...
;         for (int ps = 0; ps < 8; ++ps) {
;             const int rl = ps * 4 + (lanef >> 4); const size_t row = rowb + rl;
;             const v4u sv = *(const LAS v4u*)(stg + rl * 128 + cl * 8);
;             float xv[8];
;             xv[0] = __builtin_bit_cast(float, sv.x << 16); xv[1] = __builtin_bit_cast(float, sv.x & 0xffff0000u); xv[2] = __builtin_bit_cast(float, sv.y << 16); xv[3] = __builtin_bit_cast(float, sv.y & 0xffff0000u);
;             xv[4] = __builtin_bit_cast(float, sv.z << 16); xv[5] = __builtin_bit_cast(float, sv.z & 0xffff0000u); xv[6] = __builtin_bit_cast(float, sv.w << 16); xv[7] = __builtin_bit_cast(float, sv.w & 0xffff0000u);
;             const v4u gv = *(const v4u*)(C.GD + row * 512 + h * 128 + cl * 8);
;             float gg[8];
;             gg[0] = __builtin_bit_cast(float, gv.x << 16); gg[1] = __builtin_bit_cast(float, gv.x & 0xffff0000u); gg[2] = __builtin_bit_cast(float, gv.y << 16); gg[3] = __builtin_bit_cast(float, gv.y & 0xffff0000u);
;             gg[4] = __builtin_bit_cast(float, gv.z << 16); gg[5] = __builtin_bit_cast(float, gv.z & 0xffff0000u); gg[6] = __builtin_bit_cast(float, gv.w << 16); gg[7] = __builtin_bit_cast(float, gv.w & 0xffff0000u);
;             float sq = 0.f;
; #pragma unroll
;             for (int e = 0; e < 8; ++e) sq += xv[e] * xv[e];
;     ...
;             SQDPP(0xB1); SQDPP(0x4E); SQDPP(0x141); SQDPP(0x140);
;     ...
;             const float rs = (1.0f / sqrtf(sq * (1.0f / 128.0f) + EPSN)) * 0.8f;
;             const f32x4 s0 = *(const f32x4*)(C.subln + cl * 8), s1 = *(const f32x4*)(C.subln + cl * 8 + 4);
; #pragma unroll
;             for (int e = 0; e < 4; ++e) { xv[e] *= rs * s0[e]; xv[4 + e] *= rs * s1[e]; }
;             v4u ov; ov.x = pk2(xv[0] * gg[0], xv[1] * gg[1]); ov.y = pk2(xv[2] * gg[2], xv[3] * gg[3]); ov.z = pk2(xv[4] * gg[4], xv[5] * gg[5]); ov.w = pk2(xv[6] * gg[6], xv[7] * gg[7]);
;             *(v4u*)(C.MIX + row * 1024 + 512 + h * 128 + cl * 8) = ov;
	v_lshlrev_b32_e32 v124, 16, v106
	v_and_b32_e32 v125, 0xffff0000, v106
	v_lshlrev_b32_e32 v120, 16, v107
	v_and_b32_e32 v121, 0xffff0000, v107
	v_pk_mul_f32 v[106:107], v[124:125], v[124:125]
	v_pk_mul_f32 v[122:123], v[120:121], v[120:121]
	v_lshlrev_b32_e32 v118, 16, v108
	v_and_b32_e32 v119, 0xffff0000, v108
	v_lshlrev_b32_e32 v112, 16, v109
	v_and_b32_e32 v113, 0xffff0000, v109
	v_pk_mul_f32 v[108:109], v[118:119], v[118:119]
	v_pk_mul_f32 v[116:117], v[112:113], v[112:113]
	s_waitcnt vmcnt(2)
	v_lshlrev_b32_e32 v114, 16, v33
	v_and_b32_e32 v115, 0xffff0000, v33
	v_add_f32_e32 v33, v106, v107
	v_add_f32_e32 v33, v122, v33
	v_add_f32_e32 v33, v123, v33
	v_add_f32_e32 v33, v108, v33
	v_add_f32_e32 v33, v109, v33
	v_add_f32_e32 v33, v116, v33
	v_add_f32_e32 v33, v117, v33
	v_and_b32_e32 v107, 0xffff0000, v32
	s_nop 0
	v_add_f32_dpp v33, v33, v33 quad_perm:[1,0,3,2] row_mask:0xf bank_mask:0xf bound_ctrl:1
	s_nop 1
	v_add_f32_dpp v33, v33, v33 quad_perm:[2,3,0,1] row_mask:0xf bank_mask:0xf bound_ctrl:1
	s_nop 1
	v_add_f32_dpp v33, v33, v33 row_half_mirror row_mask:0xf bank_mask:0xf bound_ctrl:1
	s_nop 1
	v_add_f32_dpp v33, v33, v33 row_mirror row_mask:0xf bank_mask:0xf bound_ctrl:1
	v_fmamk_f32 v33, v33, 0x3c000000, v217
	v_mul_f32_e32 v106, 0x4f800000, v33
	v_cmp_gt_f32_e32 vcc, s56, v33
	s_nop 1
	v_cndmask_b32_e32 v33, v33, v106, vcc
	v_sqrt_f32_e32 v108, v33
	v_lshlrev_b32_e32 v106, 16, v32
	v_lshlrev_b32_e32 v32, 16, v31
	v_add_u32_e32 v109, -1, v108
	v_fma_f32 v116, -v109, v108, v33
	v_cmp_ge_f32_e64 s[2:3], 0, v116
	v_add_u32_e32 v116, 1, v108
	s_nop 0
	v_cndmask_b32_e64 v109, v108, v109, s[2:3]
	v_fma_f32 v108, -v116, v108, v33
	v_cmp_lt_f32_e64 s[2:3], 0, v108
	s_nop 1
	v_cndmask_b32_e64 v108, v109, v116, s[2:3]
	v_mul_f32_e32 v109, 0x37800000, v108
	v_cndmask_b32_e32 v108, v108, v109, vcc
	v_cmp_class_f32_e32 vcc, v33, v228
	v_and_b32_e32 v109, 0xffff0000, v30
	s_nop 0
	v_cndmask_b32_e32 v116, v108, v33, vcc
	v_div_scale_f32 v117, s[0:1], v116, v116, 1.0
	v_rcp_f32_e32 v122, v117
	v_lshlrev_b32_e32 v108, 16, v30
	v_and_b32_e32 v33, 0xffff0000, v31
	v_fma_f32 v30, -v117, v122, 1.0
	v_fmac_f32_e32 v122, v30, v122
	v_div_scale_f32 v30, vcc, 1.0, v116, 1.0
	v_mul_f32_e32 v31, v30, v122
	v_fma_f32 v123, -v117, v31, v30
	v_fmac_f32_e32 v31, v123, v122
	v_fma_f32 v30, -v117, v31, v30
	v_div_fmas_f32 v30, v30, v122, v31
	v_div_fixup_f32 v30, v30, v116, 1.0
	v_mul_f32_e32 v30, 0x3f4ccccd, v30
	s_waitcnt vmcnt(1)
	v_pk_mul_f32 v[98:99], v[98:99], v[30:31] op_sel_hi:[1,0]
	v_pk_mul_f32 v[100:101], v[100:101], v[30:31] op_sel_hi:[1,0]
	v_pk_mul_f32 v[98:99], v[98:99], v[124:125]
	s_waitcnt vmcnt(0)
	v_pk_mul_f32 v[102:103], v[102:103], v[30:31] op_sel_hi:[1,0]
	v_pk_mul_f32 v[100:101], v[100:101], v[120:121]
	v_pk_mul_f32 v[30:31], v[104:105], v[30:31] op_sel_hi:[1,0]
	v_pk_mul_f32 v[102:103], v[102:103], v[118:119]
	v_pk_mul_f32 v[104:105], v[30:31], v[112:113]
	v_pk_mul_f32 v[30:31], v[98:99], v[108:109]
	v_pk_mul_f32 v[32:33], v[100:101], v[32:33]
	v_cvt_pk_bf16_f32 v30, v30, v31
	v_cvt_pk_bf16_f32 v31, v32, v33
	v_pk_mul_f32 v[32:33], v[102:103], v[106:107]
	v_pk_mul_f32 v[98:99], v[104:105], v[114:115]
	v_cvt_pk_bf16_f32 v32, v32, v33
	v_cvt_pk_bf16_f32 v33, v98, v99
	v_lshlrev_b64 v[98:99], 11, v[110:111]
	v_lshl_add_u64 v[98:99], s[4:5], 0, v[98:99]
	v_lshl_add_u64 v[98:99], v[98:99], 0, v[218:219]
	v_or_b32_e32 v106, 20, v6
	v_lshl_add_u64 v[98:99], v[98:99], 0, v[4:5]
	v_or_b32_e32 v110, v16, v106
	global_store_dwordx4 v[98:99], v[30:33], off offset:1024
	v_lshl_add_u32 v106, v106, 8, v9
	s_nop 0
	v_lshlrev_b64 v[30:31], 10, v[110:111]
	v_lshl_add_u64 v[30:31], s[6:7], 0, v[30:31]
	v_lshl_add_u64 v[30:31], v[30:31], 0, v[218:219]
	v_lshl_add_u64 v[30:31], v[30:31], 0, v[4:5]
	global_load_dwordx4 v[30:33], v[30:31], off
	s_nop 0
	global_load_dwordx4 v[98:101], v7, s[72:73]
	global_load_dwordx4 v[102:105], v7, s[72:73] offset:16
	ds_read_b128 v[106:109], v106
	s_waitcnt lgkmcnt(0)
	v_lshlrev_b32_e32 v124, 16, v106
	v_and_b32_e32 v125, 0xffff0000, v106
	v_lshlrev_b32_e32 v120, 16, v107
	v_and_b32_e32 v121, 0xffff0000, v107
	v_pk_mul_f32 v[106:107], v[124:125], v[124:125]
	v_pk_mul_f32 v[122:123], v[120:121], v[120:121]
	v_lshlrev_b32_e32 v118, 16, v108
	v_and_b32_e32 v119, 0xffff0000, v108
	v_lshlrev_b32_e32 v112, 16, v109
	v_and_b32_e32 v113, 0xffff0000, v109
	v_pk_mul_f32 v[108:109], v[118:119], v[118:119]
	v_pk_mul_f32 v[116:117], v[112:113], v[112:113]
	s_waitcnt vmcnt(2)
	v_lshlrev_b32_e32 v114, 16, v33
	v_and_b32_e32 v115, 0xffff0000, v33
	v_add_f32_e32 v33, v106, v107
	v_add_f32_e32 v33, v122, v33
	v_add_f32_e32 v33, v123, v33
	v_add_f32_e32 v33, v108, v33
	v_add_f32_e32 v33, v109, v33
	v_add_f32_e32 v33, v116, v33
	v_add_f32_e32 v33, v117, v33
	v_and_b32_e32 v107, 0xffff0000, v32
	s_nop 0
	v_add_f32_dpp v33, v33, v33 quad_perm:[1,0,3,2] row_mask:0xf bank_mask:0xf bound_ctrl:1
	s_nop 1
	v_add_f32_dpp v33, v33, v33 quad_perm:[2,3,0,1] row_mask:0xf bank_mask:0xf bound_ctrl:1
	s_nop 1
	v_add_f32_dpp v33, v33, v33 row_half_mirror row_mask:0xf bank_mask:0xf bound_ctrl:1
	s_nop 1
	v_add_f32_dpp v33, v33, v33 row_mirror row_mask:0xf bank_mask:0xf bound_ctrl:1
	v_fmamk_f32 v33, v33, 0x3c000000, v217
	v_mul_f32_e32 v106, 0x4f800000, v33
	v_cmp_gt_f32_e32 vcc, s56, v33
	s_nop 1
	v_cndmask_b32_e32 v33, v33, v106, vcc
	v_sqrt_f32_e32 v108, v33
	v_lshlrev_b32_e32 v106, 16, v32
	v_lshlrev_b32_e32 v32, 16, v31
	v_add_u32_e32 v109, -1, v108
	v_fma_f32 v116, -v109, v108, v33
	v_cmp_ge_f32_e64 s[2:3], 0, v116
	v_add_u32_e32 v116, 1, v108
	s_nop 0
	v_cndmask_b32_e64 v109, v108, v109, s[2:3]
	v_fma_f32 v108, -v116, v108, v33
	v_cmp_lt_f32_e64 s[2:3], 0, v108
	s_nop 1
	v_cndmask_b32_e64 v108, v109, v116, s[2:3]
	v_mul_f32_e32 v109, 0x37800000, v108
	v_cndmask_b32_e32 v108, v108, v109, vcc
	v_cmp_class_f32_e32 vcc, v33, v228
	v_and_b32_e32 v109, 0xffff0000, v30
	s_nop 0
	v_cndmask_b32_e32 v116, v108, v33, vcc
	v_div_scale_f32 v117, s[0:1], v116, v116, 1.0
	v_rcp_f32_e32 v122, v117
	v_lshlrev_b32_e32 v108, 16, v30
	v_and_b32_e32 v33, 0xffff0000, v31
	v_fma_f32 v30, -v117, v122, 1.0
	v_fmac_f32_e32 v122, v30, v122
	v_div_scale_f32 v30, vcc, 1.0, v116, 1.0
	v_mul_f32_e32 v31, v30, v122
	v_fma_f32 v123, -v117, v31, v30
	v_fmac_f32_e32 v31, v123, v122
	v_fma_f32 v30, -v117, v31, v30
	v_div_fmas_f32 v30, v30, v122, v31
	v_div_fixup_f32 v30, v30, v116, 1.0
	v_mul_f32_e32 v30, 0x3f4ccccd, v30
	s_waitcnt vmcnt(1)
; #define LAS __attribute__((address_space(3)))
; __device__ __forceinline__ unsigned pk2(float lo, float hi) { f32x2_t v = {lo, hi}; bf16x2_t b = __builtin_convertvector(v, bf16x2_t); return __builtin_bit_cast(unsigned, b); }
; template <bool NOMAX>
; __device__ __forceinline__ void diff_unit(const AttnCtx& C, int u, LAS unsigned char* lds) {
;     ...
;         for (int ps = 0; ps < 8; ++ps) {
;             const int rl = ps * 4 + (lanef >> 4); const size_t row = rowb + rl;
;             const v4u sv = *(const LAS v4u*)(stg + rl * 128 + cl * 8);
;             float xv[8];
;             xv[0] = __builtin_bit_cast(float, sv.x << 16); xv[1] = __builtin_bit_cast(float, sv.x & 0xffff0000u); xv[2] = __builtin_bit_cast(float, sv.y << 16); xv[3] = __builtin_bit_cast(float, sv.y & 0xffff0000u);
;             xv[4] = __builtin_bit_cast(float, sv.z << 16); xv[5] = __builtin_bit_cast(float, sv.z & 0xffff0000u); xv[6] = __builtin_bit_cast(float, sv.w << 16); xv[7] = __builtin_bit_cast(float, sv.w & 0xffff0000u);
;             const v4u gv = *(const v4u*)(C.GD + row * 512 + h * 128 + cl * 8);
;             float gg[8];
;             gg[0] = __builtin_bit_cast(float, gv.x << 16); gg[1] = __builtin_bit_cast(float, gv.x & 0xffff0000u); gg[2] = __builtin_bit_cast(float, gv.y << 16); gg[3] = __builtin_bit_cast(float, gv.y & 0xffff0000u);
;             gg[4] = __builtin_bit_cast(float, gv.z << 16); gg[5] = __builtin_bit_cast(float, gv.z & 0xffff0000u); gg[6] = __builtin_bit_cast(float, gv.w << 16); gg[7] = __builtin_bit_cast(float, gv.w & 0xffff0000u);
;             float sq = 0.f;
; #pragma unroll
;             for (int e = 0; e < 8; ++e) sq += xv[e] * xv[e];
;     ...
;             SQDPP(0xB1); SQDPP(0x4E); SQDPP(0x141); SQDPP(0x140);
;     ...
;             const float rs = (1.0f / sqrtf(sq * (1.0f / 128.0f) + EPSN)) * 0.8f;
;             const f32x4 s0 = *(const f32x4*)(C.subln + cl * 8), s1 = *(const f32x4*)(C.subln + cl * 8 + 4);
; #pragma unroll
;             for (int e = 0; e < 4; ++e) { xv[e] *= rs * s0[e]; xv[4 + e] *= rs * s1[e]; }
;             v4u ov; ov.x = pk2(xv[0] * gg[0], xv[1] * gg[1]); ov.y = pk2(xv[2] * gg[2], xv[3] * gg[3]); ov.z = pk2(xv[4] * gg[4], xv[5] * gg[5]); ov.w = pk2(xv[6] * gg[6], xv[7] * gg[7]);
;             *(v4u*)(C.MIX + row * 1024 + 512 + h * 128 + cl * 8) = ov;
	v_pk_mul_f32 v[98:99], v[98:99], v[30:31] op_sel_hi:[1,0]
	v_pk_mul_f32 v[100:101], v[100:101], v[30:31] op_sel_hi:[1,0]
	v_pk_mul_f32 v[98:99], v[98:99], v[124:125]
	s_waitcnt vmcnt(0)
	v_pk_mul_f32 v[102:103], v[102:103], v[30:31] op_sel_hi:[1,0]
	v_pk_mul_f32 v[100:101], v[100:101], v[120:121]
	v_pk_mul_f32 v[30:31], v[104:105], v[30:31] op_sel_hi:[1,0]
	v_pk_mul_f32 v[102:103], v[102:103], v[118:119]
	v_pk_mul_f32 v[104:105], v[30:31], v[112:113]
	v_pk_mul_f32 v[30:31], v[98:99], v[108:109]
	v_pk_mul_f32 v[32:33], v[100:101], v[32:33]
	v_cvt_pk_bf16_f32 v30, v30, v31
	v_cvt_pk_bf16_f32 v31, v32, v33
	v_pk_mul_f32 v[32:33], v[102:103], v[106:107]
	v_pk_mul_f32 v[98:99], v[104:105], v[114:115]
	v_cvt_pk_bf16_f32 v32, v32, v33
	v_cvt_pk_bf16_f32 v33, v98, v99
	v_lshlrev_b64 v[98:99], 11, v[110:111]
	v_lshl_add_u64 v[98:99], s[4:5], 0, v[98:99]
	v_lshl_add_u64 v[98:99], v[98:99], 0, v[218:219]
	v_or_b32_e32 v106, 24, v6
	v_lshl_add_u64 v[98:99], v[98:99], 0, v[4:5]
	v_or_b32_e32 v110, v16, v106
	global_store_dwordx4 v[98:99], v[30:33], off offset:1024
	v_lshl_add_u32 v106, v106, 8, v9
	v_or_b32_e32 v6, 28, v6
	v_lshlrev_b64 v[30:31], 10, v[110:111]
	v_lshl_add_u64 v[30:31], s[6:7], 0, v[30:31]
	v_lshl_add_u64 v[30:31], v[30:31], 0, v[218:219]
	v_lshl_add_u64 v[30:31], v[30:31], 0, v[4:5]
	global_load_dwordx4 v[30:33], v[30:31], off
	s_nop 0
	global_load_dwordx4 v[98:101], v7, s[72:73]
	global_load_dwordx4 v[102:105], v7, s[72:73] offset:16
	ds_read_b128 v[106:109], v106
	v_or_b32_e32 v16, v16, v6
	v_lshl_add_u32 v6, v6, 8, v9
	s_waitcnt lgkmcnt(0)
	v_lshlrev_b32_e32 v124, 16, v106
	v_and_b32_e32 v125, 0xffff0000, v106
	v_lshlrev_b32_e32 v120, 16, v107
	v_and_b32_e32 v121, 0xffff0000, v107
	v_pk_mul_f32 v[106:107], v[124:125], v[124:125]
	v_pk_mul_f32 v[122:123], v[120:121], v[120:121]
	v_lshlrev_b32_e32 v118, 16, v108
	v_and_b32_e32 v119, 0xffff0000, v108
	v_lshlrev_b32_e32 v112, 16, v109
	v_and_b32_e32 v113, 0xffff0000, v109
	v_pk_mul_f32 v[108:109], v[118:119], v[118:119]
	v_pk_mul_f32 v[116:117], v[112:113], v[112:113]
	s_waitcnt vmcnt(2)
	v_lshlrev_b32_e32 v114, 16, v33
	v_and_b32_e32 v115, 0xffff0000, v33
	v_add_f32_e32 v33, v106, v107
	v_add_f32_e32 v33, v122, v33
	v_add_f32_e32 v33, v123, v33
	v_add_f32_e32 v33, v108, v33
	v_add_f32_e32 v33, v109, v33
	v_add_f32_e32 v33, v116, v33
	v_add_f32_e32 v33, v117, v33
	v_and_b32_e32 v107, 0xffff0000, v32
	s_nop 0
	v_add_f32_dpp v33, v33, v33 quad_perm:[1,0,3,2] row_mask:0xf bank_mask:0xf bound_ctrl:1
	s_nop 1
	v_add_f32_dpp v33, v33, v33 quad_perm:[2,3,0,1] row_mask:0xf bank_mask:0xf bound_ctrl:1
	s_nop 1
	v_add_f32_dpp v33, v33, v33 row_half_mirror row_mask:0xf bank_mask:0xf bound_ctrl:1
	s_nop 1
	v_add_f32_dpp v33, v33, v33 row_mirror row_mask:0xf bank_mask:0xf bound_ctrl:1
	v_fmamk_f32 v33, v33, 0x3c000000, v217
	v_mul_f32_e32 v106, 0x4f800000, v33
	v_cmp_gt_f32_e32 vcc, s56, v33
	s_nop 1
	v_cndmask_b32_e32 v33, v33, v106, vcc
	v_sqrt_f32_e32 v108, v33
	v_lshlrev_b32_e32 v106, 16, v32
	v_lshlrev_b32_e32 v32, 16, v31
	v_add_u32_e32 v109, -1, v108
	v_fma_f32 v116, -v109, v108, v33
	v_cmp_ge_f32_e64 s[2:3], 0, v116
	v_add_u32_e32 v116, 1, v108
	s_nop 0
	v_cndmask_b32_e64 v109, v108, v109, s[2:3]
	v_fma_f32 v108, -v116, v108, v33
	v_cmp_lt_f32_e64 s[2:3], 0, v108
	s_nop 1
	v_cndmask_b32_e64 v108, v109, v116, s[2:3]
	v_mul_f32_e32 v109, 0x37800000, v108
	v_cndmask_b32_e32 v108, v108, v109, vcc
	v_cmp_class_f32_e32 vcc, v33, v228
	v_and_b32_e32 v109, 0xffff0000, v30
	s_nop 0
	v_cndmask_b32_e32 v116, v108, v33, vcc
	v_div_scale_f32 v117, s[0:1], v116, v116, 1.0
	v_rcp_f32_e32 v122, v117
	v_lshlrev_b32_e32 v108, 16, v30
	v_and_b32_e32 v33, 0xffff0000, v31
	v_fma_f32 v30, -v117, v122, 1.0
	v_fmac_f32_e32 v122, v30, v122
	v_div_scale_f32 v30, vcc, 1.0, v116, 1.0
	v_mul_f32_e32 v31, v30, v122
	v_fma_f32 v123, -v117, v31, v30
	v_fmac_f32_e32 v31, v123, v122
	v_fma_f32 v30, -v117, v31, v30
	v_div_fmas_f32 v30, v30, v122, v31
	v_div_fixup_f32 v30, v30, v116, 1.0
	v_mul_f32_e32 v30, 0x3f4ccccd, v30
	s_waitcnt vmcnt(1)
	v_pk_mul_f32 v[98:99], v[98:99], v[30:31] op_sel_hi:[1,0]
	v_pk_mul_f32 v[100:101], v[100:101], v[30:31] op_sel_hi:[1,0]
	v_pk_mul_f32 v[98:99], v[98:99], v[124:125]
	s_waitcnt vmcnt(0)
	v_pk_mul_f32 v[102:103], v[102:103], v[30:31] op_sel_hi:[1,0]
	v_pk_mul_f32 v[100:101], v[100:101], v[120:121]
	v_pk_mul_f32 v[30:31], v[104:105], v[30:31] op_sel_hi:[1,0]
	v_pk_mul_f32 v[102:103], v[102:103], v[118:119]
	v_pk_mul_f32 v[104:105], v[30:31], v[112:113]
	v_pk_mul_f32 v[30:31], v[98:99], v[108:109]
	v_pk_mul_f32 v[32:33], v[100:101], v[32:33]
	v_cvt_pk_bf16_f32 v30, v30, v31
	v_cvt_pk_bf16_f32 v31, v32, v33
	v_pk_mul_f32 v[32:33], v[102:103], v[106:107]
	v_pk_mul_f32 v[98:99], v[104:105], v[114:115]
	v_cvt_pk_bf16_f32 v32, v32, v33
	v_cvt_pk_bf16_f32 v33, v98, v99
	v_lshlrev_b64 v[98:99], 11, v[110:111]
	v_lshl_add_u64 v[98:99], s[4:5], 0, v[98:99]
	v_lshl_add_u64 v[98:99], v[98:99], 0, v[218:219]
	v_lshl_add_u64 v[98:99], v[98:99], 0, v[4:5]
	global_store_dwordx4 v[98:99], v[30:33], off offset:1024
	s_nop 1
	v_lshlrev_b64 v[30:31], 10, v[16:17]
	v_lshl_add_u64 v[30:31], s[6:7], 0, v[30:31]
	v_lshl_add_u64 v[30:31], v[30:31], 0, v[218:219]
	v_lshl_add_u64 v[30:31], v[30:31], 0, v[4:5]
	global_load_dwordx4 v[30:33], v[30:31], off
	s_nop 0
	global_load_dwordx4 v[98:101], v7, s[72:73]
	global_load_dwordx4 v[102:105], v7, s[72:73] offset:16
	ds_read_b128 v[106:109], v6
	s_waitcnt lgkmcnt(0)
; __device__ __forceinline__ unsigned pk2(float lo, float hi) { f32x2_t v = {lo, hi}; bf16x2_t b = __builtin_convertvector(v, bf16x2_t); return __builtin_bit_cast(unsigned, b); }
; template <bool NOMAX>
; __device__ __forceinline__ void diff_unit(const AttnCtx& C, int u, LAS unsigned char* lds) {
;     ...
;     if (umap == 0) {
;         f32x4* st = (f32x4*)(C.stash + (slot * 512 + tidf) * 64);
; #pragma unroll
;         for (int d = 0; d < 4; ++d)
; #pragma unroll
;             for (int gq = 0; gq < 4; ++gq) st[d * 4 + gq] = (f32x4){o[d][4 * gq] * rli[4 * gq], o[d][4 * gq + 1] * rli[4 * gq + 1], o[d][4 * gq + 2] * rli[4 * gq + 2], o[d][4 * gq + 3] * rli[4 * gq + 3]};
;         asm volatile("s_waitcnt vmcnt(0)" ::: "memory");
;         __syncthreads();
;         if (tidf == 0) { __builtin_amdgcn_fence(__ATOMIC_RELEASE, "agent"); asm volatile("s_waitcnt vmcnt(0)" ::: "memory");
;             __hip_atomic_store(C.flags + 16 * (qb * 4 + h), 1u, __ATOMIC_RELAXED, __HIP_MEMORY_SCOPE_AGENT); }
;     ...
;             const float rs = (1.0f / sqrtf(sq * (1.0f / 128.0f) + EPSN)) * 0.8f;
;             const f32x4 s0 = *(const f32x4*)(C.subln + cl * 8), s1 = *(const f32x4*)(C.subln + cl * 8 + 4);
; #pragma unroll
;             for (int e = 0; e < 4; ++e) { xv[e] *= rs * s0[e]; xv[4 + e] *= rs * s1[e]; }
;             v4u ov; ov.x = pk2(xv[0] * gg[0], xv[1] * gg[1]); ov.y = pk2(xv[2] * gg[2], xv[3] * gg[3]); ov.z = pk2(xv[4] * gg[4], xv[5] * gg[5]); ov.w = pk2(xv[6] * gg[6], xv[7] * gg[7]);
;             *(v4u*)(C.MIX + row * 1024 + 512 + h * 128 + cl * 8) = ov;
	v_lshlrev_b32_e32 v120, 16, v106
	v_and_b32_e32 v121, 0xffff0000, v106
	v_lshlrev_b32_e32 v116, 16, v107
	v_and_b32_e32 v117, 0xffff0000, v107
	v_pk_mul_f32 v[106:107], v[120:121], v[120:121]
	v_pk_mul_f32 v[118:119], v[116:117], v[116:117]
	v_add_f32_e32 v9, v106, v107
	v_lshlrev_b32_e32 v114, 16, v108
	v_and_b32_e32 v115, 0xffff0000, v108
	v_add_f32_e32 v9, v118, v9
	v_lshlrev_b32_e32 v6, 16, v109
	v_and_b32_e32 v7, 0xffff0000, v109
	v_pk_mul_f32 v[108:109], v[114:115], v[114:115]
	v_add_f32_e32 v9, v119, v9
	v_add_f32_e32 v9, v108, v9
	v_pk_mul_f32 v[112:113], v[6:7], v[6:7]
	v_add_f32_e32 v9, v109, v9
	v_add_f32_e32 v9, v112, v9
	v_add_f32_e32 v9, v113, v9
	s_waitcnt vmcnt(2)
	v_lshlrev_b32_e32 v110, 16, v33
	v_add_f32_dpp v9, v9, v9 quad_perm:[1,0,3,2] row_mask:0xf bank_mask:0xf bound_ctrl:1
	v_and_b32_e32 v111, 0xffff0000, v33
	v_lshlrev_b32_e32 v106, 16, v32
	v_add_f32_dpp v9, v9, v9 quad_perm:[2,3,0,1] row_mask:0xf bank_mask:0xf bound_ctrl:1
	v_and_b32_e32 v107, 0xffff0000, v32
	v_lshlrev_b32_e32 v32, 16, v31
	v_add_f32_dpp v9, v9, v9 row_half_mirror row_mask:0xf bank_mask:0xf bound_ctrl:1
	s_nop 1
	v_add_f32_dpp v9, v9, v9 row_mirror row_mask:0xf bank_mask:0xf bound_ctrl:1
	v_fmamk_f32 v9, v9, 0x3c000000, v217
	v_mul_f32_e32 v33, 0x4f800000, v9
	v_cmp_gt_f32_e32 vcc, s56, v9
	s_nop 1
	v_cndmask_b32_e32 v9, v9, v33, vcc
	v_sqrt_f32_e32 v33, v9
	s_nop 0
	v_add_u32_e32 v108, -1, v33
	v_fma_f32 v109, -v108, v33, v9
	v_cmp_ge_f32_e64 s[2:3], 0, v109
	v_add_u32_e32 v109, 1, v33
	s_nop 0
	v_cndmask_b32_e64 v108, v33, v108, s[2:3]
	v_fma_f32 v33, -v109, v33, v9
	v_cmp_lt_f32_e64 s[2:3], 0, v33
	s_nop 1
	v_cndmask_b32_e64 v33, v108, v109, s[2:3]
	v_mul_f32_e32 v108, 0x37800000, v33
	v_cndmask_b32_e32 v33, v33, v108, vcc
	v_cmp_class_f32_e32 vcc, v9, v228
	v_lshlrev_b32_e32 v108, 16, v30
	v_and_b32_e32 v109, 0xffff0000, v30
	v_cndmask_b32_e32 v9, v33, v9, vcc
	v_div_scale_f32 v112, s[0:1], v9, v9, 1.0
	v_rcp_f32_e32 v113, v112
	v_and_b32_e32 v33, 0xffff0000, v31
	v_fma_f32 v30, -v112, v113, 1.0
	v_fmac_f32_e32 v113, v30, v113
	v_div_scale_f32 v30, vcc, 1.0, v9, 1.0
	v_mul_f32_e32 v31, v30, v113
	v_fma_f32 v118, -v112, v31, v30
	v_fmac_f32_e32 v31, v118, v113
	v_fma_f32 v30, -v112, v31, v30
	v_div_fmas_f32 v30, v30, v113, v31
	v_div_fixup_f32 v9, v30, v9, 1.0
	v_mul_f32_e32 v30, 0x3f4ccccd, v9
	s_waitcnt vmcnt(1)
	v_pk_mul_f32 v[98:99], v[98:99], v[30:31] op_sel_hi:[1,0]
	v_pk_mul_f32 v[100:101], v[100:101], v[30:31] op_sel_hi:[1,0]
	v_pk_mul_f32 v[98:99], v[98:99], v[120:121]
	s_waitcnt vmcnt(0)
	v_pk_mul_f32 v[102:103], v[102:103], v[30:31] op_sel_hi:[1,0]
	v_pk_mul_f32 v[100:101], v[100:101], v[116:117]
	v_pk_mul_f32 v[30:31], v[104:105], v[30:31] op_sel_hi:[1,0]
	v_pk_mul_f32 v[102:103], v[102:103], v[114:115]
	v_pk_mul_f32 v[6:7], v[30:31], v[6:7]
	v_pk_mul_f32 v[30:31], v[98:99], v[108:109]
	v_pk_mul_f32 v[32:33], v[100:101], v[32:33]
	v_cvt_pk_bf16_f32 v30, v30, v31
	v_cvt_pk_bf16_f32 v31, v32, v33
	v_pk_mul_f32 v[32:33], v[102:103], v[106:107]
	v_pk_mul_f32 v[6:7], v[6:7], v[110:111]
	v_cvt_pk_bf16_f32 v32, v32, v33
	v_cvt_pk_bf16_f32 v33, v6, v7
	v_lshlrev_b64 v[6:7], 11, v[16:17]
	v_lshl_add_u64 v[6:7], s[4:5], 0, v[6:7]
	v_lshl_add_u64 v[6:7], v[6:7], 0, v[218:219]
	v_lshl_add_u64 v[4:5], v[6:7], 0, v[4:5]
	s_mov_b64 s[4:5], 0
	global_store_dwordx4 v[4:5], v[30:33], off offset:1024
.LBB0_641:
	s_and_b64 vcc, exec, s[4:5]
	s_cbranch_vccz .LBB0_446
	v_ashrrev_i32_e32 v9, 31, v8
	v_lshlrev_b64 v[4:5], 17, v[2:3]
	v_lshl_add_u64 v[4:5], s[12:13], 0, v[4:5]
	v_and_b32_e32 v6, 63, v8
	v_lshrrev_b32_e32 v7, 6, v8
	v_lshlrev_b32_e32 v6, 4, v6
	v_lshl_add_u32 v6, v7, 14, v6
	v_add_u32_e32 v6, 0x1000, v6
	v_mov_b32_e32 v7, 0
	s_mov_b64 s[98:99], 0x2000
	v_lshl_add_u64 v[16:17], v[4:5], 0, v[6:7]
	v_lshl_add_u64 v[254:255], v[16:17], 0, s[98:99]
	v_pk_mul_f32 v[4:5], v[82:83], v[28:29]
	v_pk_mul_f32 v[6:7], v[84:85], v[26:27]
	global_store_dwordx4 v[16:17], v[4:7], off offset:-4096
	v_cmp_eq_u32_e32 vcc, 0, v8
	s_nop 0
	v_pk_mul_f32 v[4:5], v[86:87], v[14:15]
	v_pk_mul_f32 v[6:7], v[88:89], v[24:25]
	global_store_dwordx4 v[16:17], v[4:7], off offset:-3072
	s_nop 1
	v_pk_mul_f32 v[4:5], v[90:91], v[22:23]
	v_pk_mul_f32 v[6:7], v[92:93], v[20:21]
	global_store_dwordx4 v[16:17], v[4:7], off offset:-2048
	s_nop 1
	v_pk_mul_f32 v[4:5], v[94:95], v[12:13]
	v_pk_mul_f32 v[6:7], v[96:97], v[10:11]
	global_store_dwordx4 v[16:17], v[4:7], off offset:-1024
	s_nop 1
	v_pk_mul_f32 v[4:5], v[66:67], v[28:29]
	v_pk_mul_f32 v[6:7], v[68:69], v[26:27]
	global_store_dwordx4 v[16:17], v[4:7], off
	s_nop 1
	v_pk_mul_f32 v[4:5], v[70:71], v[14:15]
	v_pk_mul_f32 v[6:7], v[72:73], v[24:25]
	global_store_dwordx4 v[16:17], v[4:7], off offset:1024
	s_nop 1
	v_pk_mul_f32 v[4:5], v[74:75], v[22:23]
	v_pk_mul_f32 v[6:7], v[76:77], v[20:21]
	global_store_dwordx4 v[16:17], v[4:7], off offset:2048
	s_nop 1
	v_pk_mul_f32 v[4:5], v[78:79], v[12:13]
	v_pk_mul_f32 v[6:7], v[80:81], v[10:11]
	global_store_dwordx4 v[16:17], v[4:7], off offset:3072
	s_nop 1
	v_pk_mul_f32 v[4:5], v[50:51], v[28:29]
	v_pk_mul_f32 v[6:7], v[52:53], v[26:27]
	global_store_dwordx4 v[254:255], v[4:7], off offset:-4096
	s_nop 1
	v_pk_mul_f32 v[4:5], v[54:55], v[14:15]
	v_pk_mul_f32 v[6:7], v[56:57], v[24:25]
	global_store_dwordx4 v[254:255], v[4:7], off offset:-3072
	s_nop 1
	v_pk_mul_f32 v[4:5], v[58:59], v[22:23]
	v_pk_mul_f32 v[6:7], v[60:61], v[20:21]
	global_store_dwordx4 v[254:255], v[4:7], off offset:-2048
	s_nop 1
	v_pk_mul_f32 v[4:5], v[62:63], v[12:13]
	v_pk_mul_f32 v[6:7], v[64:65], v[10:11]
	global_store_dwordx4 v[254:255], v[4:7], off offset:-1024
	s_nop 1
	v_pk_mul_f32 v[4:5], v[34:35], v[28:29]
	v_pk_mul_f32 v[6:7], v[36:37], v[26:27]
	global_store_dwordx4 v[254:255], v[4:7], off
	s_nop 1
	v_pk_mul_f32 v[4:5], v[38:39], v[14:15]
	v_pk_mul_f32 v[6:7], v[40:41], v[24:25]
	global_store_dwordx4 v[254:255], v[4:7], off offset:1024
	s_nop 1
	v_pk_mul_f32 v[4:5], v[42:43], v[22:23]
	v_pk_mul_f32 v[6:7], v[44:45], v[20:21]
	global_store_dwordx4 v[254:255], v[4:7], off offset:2048
	s_nop 1
	v_pk_mul_f32 v[4:5], v[46:47], v[12:13]
	v_pk_mul_f32 v[6:7], v[48:49], v[10:11]
	global_store_dwordx4 v[254:255], v[4:7], off offset:3072
	s_waitcnt vmcnt(0)
	s_barrier
	s_and_saveexec_b64 s[2:3], vcc
	s_cbranch_execz .LBB0_445
	v_lshlrev_b32_e32 v2, 4, v19
	buffer_wbl2 sc1
	s_waitcnt vmcnt(0)
	s_waitcnt vmcnt(0)
	v_lshlrev_b64 v[4:5], 2, v[2:3]
	v_lshl_add_u64 v[4:5], s[14:15], 0, v[4:5]
	global_store_dword v[4:5], v229, off sc1
	s_branch .LBB0_445
